# dropped placeholder nops that guard no hazard in hoisted scan prologues; pass A a-operand LDS reads prefetched
# speedup vs baseline: 1.0221x; 1.0038x over previous
; #define lane LANE_()
; template <int MODE>
; __device__ __forceinline__ void scan_prologue(const ScanP& P, int m0, int seqbase, int T, int h, int d, float* slab, LAS float* lw, float* bon, int lane) {
;     const int fr = lane & 15, fq = lane >> 4, m = m0 + fr, pos = m - seqbase; const bool hp = pos > 0, hn = pos < T - 1;
;     float* srow = slab + fr * 384;
;     f32x4 k4[4], kk4[4], r4[4]; float ss = 0.f;
;     v2u pk_[4][3], pv_[4][3], pr_[4][3];
;     const int offp_ = hp ? -PRP : 0, offn_ = hn ? PRP : 0; const unsigned mp_ = hp ? 0xffffffffu : 0u, mn_ = hn ? 0xffffffffu : 0u;
; #pragma unroll
;     for (int n = 0; n < 4; ++n) { const bf16* p = P.proj + (size_t)m * PRP + h * 64 + 16 * n + 4 * fq;
;         { v2u t; pk_[n][1] = *(const v2u*)(p + 512);
;           t = *(const v2u*)(p + 512 + offp_); pk_[n][0] = (v2u){t.x & mp_, t.y & mp_};
;           t = *(const v2u*)(p + 512 + offn_); pk_[n][2] = (v2u){t.x & mn_, t.y & mn_};
;           if (MODE != 1) { pv_[n][1] = *(const v2u*)(p + 1024);
;             t = *(const v2u*)(p + 1024 + offp_); pv_[n][0] = (v2u){t.x & mp_, t.y & mp_};
;             t = *(const v2u*)(p + 1024 + offn_); pv_[n][2] = (v2u){t.x & mn_, t.y & mn_}; }
;           if (MODE == 2) { pr_[n][1] = *(const v2u*)(p);
;             t = *(const v2u*)(p + offp_); pr_[n][0] = (v2u){t.x & mp_, t.y & mp_};
;             t = *(const v2u*)(p + offn_); pr_[n][2] = (v2u){t.x & mn_, t.y & mn_}; } } }
;     v4u xw_[2]; bf16x8 xa_[2];
; #pragma unroll
;     for (int ks = 0; ks < 2; ++ks) { xw_[ks] = *(const v4u*)(P.proj + (size_t)m * PRP + 1536 + d * 64 + ks * 32 + 8 * fq); xa_[ks] = *(const bf16x8*)(P.proj + (size_t)m * PRP + 1664 + d * 64 + ks * 32 + 8 * fq); }
.LBB0_289:
	s_not_b32 s4, s61
	s_add_i32 s14, s53, s4
	s_and_b64 s[4:5], s[82:83], exec
	s_cselect_b32 s4, s61, s14
	s_lshl_b32 s4, s4, 4
	v_mov_b32_e32 v212, v172
	s_add_i32 s4, s4, s52
	s_lshl_b32 s14, s87, 1
	v_and_b32_e32 v231, 15, v212
	v_or_b32_e32 v128, s4, v231
	s_waitcnt vmcnt(0)
	v_subrev_u32_e32 v129, s86, v128
	v_cmp_lt_i32_e64 s[4:5], 0, v129
	v_cmp_gt_i32_e32 vcc, s49, v129
	v_ashrrev_i32_e32 v129, 31, v128
	v_ashrrev_i32_e32 v138, 4, v212
	v_lshlrev_b64 v[128:129], 12, v[128:129]
	v_lshl_add_u64 v[128:129], s[64:65], 0, v[128:129]
	v_lshlrev_b32_e32 v154, 2, v138
	v_lshl_add_u64 v[132:133], v[128:129], 0, s[14:15]
	v_ashrrev_i32_e32 v155, 31, v154
	v_cndmask_b32_e64 v131, 0, -1, s[4:5]
	v_cndmask_b32_e64 v130, 0, v224, s[4:5]
	v_lshl_add_u64 v[132:133], v[154:155], 1, v[132:133]
	v_lshl_add_u64 v[130:131], v[132:133], 0, v[130:131]
	global_load_dwordx2 v[134:135], v[130:131], off offset:1024
	global_load_dwordx2 v[166:167], v[132:133], off offset:2048
	global_load_dwordx2 v[140:141], v[130:131], off offset:2048
	global_load_dwordx2 v[156:157], v[132:133], off offset:1056
	global_load_dwordx2 v[142:143], v[130:131], off offset:1056
	global_load_dwordx2 v[254:255], v[132:133], off offset:2080
	global_load_dwordx2 v[146:147], v[130:131], off offset:2080
	global_load_dwordx2 v[150:151], v[130:131], off offset:1088
	global_load_dwordx2 v[160:161], v[130:131], off offset:2112
	global_load_dwordx2 v[184:185], v[130:131], off offset:1120
	global_load_dwordx2 v[204:205], v[130:131], off offset:2144
	global_load_dwordx2 v[170:171], v[132:133], off offset:1024
	s_nop 0
	v_cndmask_b32_e32 v180, 0, v219, vcc
	v_mul_u32_u24_e32 v158, 0x180, v231
	s_mov_b32 s85, s15
	v_lshlrev_b32_e32 v164, 3, v138
	v_lshl_add_u64 v[128:129], v[128:129], 0, s[84:85]
	v_ashrrev_i32_e32 v165, 31, v164
	s_mov_b32 s91, 15
	s_waitcnt vmcnt(0)
	v_lshlrev_b32_e32 v240, 16, v170
	v_cndmask_b32_e64 v230, 0, v134, s[4:5]
	v_cndmask_b32_e64 v234, 0, v135, s[4:5]
	v_lshl_add_u64 v[134:135], v[132:133], 0, v[180:181]
	global_load_dwordx2 v[138:139], v[134:135], off offset:2048
	global_load_dwordx2 v[144:145], v[134:135], off offset:1056
	global_load_dwordx2 v[148:149], v[134:135], off offset:2080
	global_load_dwordx2 v[152:153], v[134:135], off offset:1088
	global_load_dwordx2 v[162:163], v[134:135], off offset:2112
	global_load_dwordx2 v[186:187], v[134:135], off offset:1120
	global_load_dwordx2 v[206:207], v[134:135], off offset:2144
	global_load_dwordx2 v[136:137], v[134:135], off offset:1024
	v_lshlrev_b32_e32 v180, 2, v158
	v_lshl_add_u32 v158, v212, 4, s94
	v_lshl_add_u64 v[176:177], s[62:63], 0, v[180:181]
	v_add_u32_e32 v180, 0x2400, v158
	v_add_u32_e32 v158, s87, v154
	v_ashrrev_i32_e32 v159, 31, v158
	v_lshlrev_b64 v[168:169], 2, v[158:159]
	v_lshl_add_u64 v[158:159], s[8:9], 0, v[168:169]
	v_and_b32_e32 v241, 0xffff0000, v170
	v_lshlrev_b32_e32 v170, 16, v171
	v_and_b32_e32 v171, 0xffff0000, v171
	v_lshlrev_b32_e32 v232, 16, v230
	v_and_b32_e32 v233, 0xffff0000, v230
	v_lshlrev_b32_e32 v238, 16, v234
	v_and_b32_e32 v239, 0xffff0000, v234
	v_lshl_add_u64 v[176:177], v[154:155], 2, v[176:177]
	v_and_b32_e32 v154, -16, v212
	v_add_u32_e32 v234, s94, v154
	v_add_u32_e32 v154, 0x2000, v234
	s_waitcnt vmcnt(0)
	v_cndmask_b32_e32 v237, 0, v136, vcc
	v_cndmask_b32_e32 v242, 0, v137, vcc
	s_nop 0
	s_nop 0
	v_cndmask_b32_e64 v203, 0, v140, s[4:5]
	v_cndmask_b32_e64 v202, 0, v141, s[4:5]
	s_nop 0
	v_lshlrev_b32_e32 v246, 16, v202
	v_and_b32_e32 v247, 0xffff0000, v202
	v_lshlrev_b32_e32 v202, 16, v166
	v_cndmask_b32_e32 v195, 0, v138, vcc
	v_cndmask_b32_e32 v193, 0, v139, vcc
	s_nop 0
	s_nop 0
	v_cndmask_b32_e64 v201, 0, v142, s[4:5]
	v_cndmask_b32_e64 v200, 0, v143, s[4:5]
	s_nop 0
	v_lshlrev_b32_e32 v250, 16, v200
	v_and_b32_e32 v251, 0xffff0000, v200
	v_lshlrev_b32_e32 v200, 16, v156
	v_cndmask_b32_e32 v194, 0, v144, vcc
	v_cndmask_b32_e32 v192, 0, v145, vcc
	s_nop 0
	s_nop 0
	v_cndmask_b32_e64 v189, 0, v146, s[4:5]
	v_cndmask_b32_e64 v188, 0, v147, s[4:5]
	global_load_dwordx2 v[146:147], v[132:133], off offset:2112
	s_nop 0
	v_cndmask_b32_e32 v179, 0, v148, vcc
	v_cndmask_b32_e32 v178, 0, v149, vcc
	global_load_dwordx2 v[148:149], v[132:133], off offset:1088
	s_nop 0
	v_cndmask_b32_e64 v199, 0, v150, s[4:5]
	v_cndmask_b32_e64 v198, 0, v151, s[4:5]
	global_load_dwordx2 v[150:151], v[132:133], off offset:1120
	s_nop 0
	v_cndmask_b32_e32 v191, 0, v152, vcc
	v_cndmask_b32_e32 v190, 0, v153, vcc
	global_load_dwordx2 v[152:153], v[132:133], off offset:2144
	s_nop 0
	s_nop 0
	v_cndmask_b32_e64 v197, 0, v160, s[4:5]
	v_cndmask_b32_e64 v196, 0, v161, s[4:5]
	s_nop 0
	v_cndmask_b32_e32 v183, 0, v162, vcc
	v_cndmask_b32_e32 v182, 0, v163, vcc
	s_nop 0
	s_nop 0
	v_cndmask_b32_e64 v214, 0, v184, s[4:5]
	v_cndmask_b32_e64 v213, 0, v185, s[4:5]
	s_nop 0
	s_nop 0
	s_nop 0
	s_nop 0
	v_lshl_add_u64 v[132:133], v[164:165], 1, v[128:129]
	global_load_dwordx4 v[140:143], v[132:133], off offset:3072
	global_load_dwordx4 v[136:139], v[132:133], off offset:3328
	global_load_dwordx4 v[128:131], v[132:133], off offset:3136
	v_cndmask_b32_e32 v216, 0, v186, vcc
	v_cndmask_b32_e64 v229, 0, v204, s[4:5]
	v_cndmask_b32_e64 v217, 0, v205, s[4:5]
	s_nop 0
	v_add_co_u32_e64 v160, s[4:5], s45, v158
	v_cndmask_b32_e32 v215, 0, v187, vcc
	global_load_dwordx4 v[184:187], v[158:159], off offset:2048
	s_nop 0
	v_addc_co_u32_e64 v161, s[4:5], 0, v159, s[4:5]
	v_add_co_u32_e64 v162, s[4:5], s96, v158
	v_cndmask_b32_e32 v236, 0, v206, vcc
	v_cndmask_b32_e32 v235, 0, v207, vcc
	global_load_dwordx4 v[204:207], v[160:161], off
	s_nop 0
	s_nop 0
	s_nop 0
	s_nop 0
	global_load_dwordx4 v[132:135], v[132:133], off offset:3392
	s_nop 0
	s_nop 0
	v_addc_co_u32_e64 v163, s[4:5], 0, v159, s[4:5]
	global_load_dwordx4 v[208:211], v[162:163], off offset:2048
	v_cmp_eq_u32_e32 vcc, s88, v231
	s_waitcnt vmcnt(2)
; #define LAS __attribute__((address_space(3)))
; #define lane LANE_()
; template <int MODE>
; __device__ __forceinline__ void scan_prologue(const ScanP& P, int m0, int seqbase, int T, int h, int d, float* slab, LAS float* lw, float* bon, int lane) {
;     ...
; #pragma unroll
;     for (int n = 0; n < 4; ++n) { const int c = 16 * n + 4 * fq, col = h * 64 + c;
;         k4[n] = CONV3_(pk_, 1);
;         if (MODE != 1) { const f32x4 v4 = CONV3_(pv_, 2); *(f32x4*)(srow + 320 + c) = v4; LAS float* xsel = (fr == (d ? 15 : 0)) ? lw + 2048 + c : lw + 2304 + lane * 4; *(LAS f32x4*)(xsel + 192) = v4; }
;         if (MODE == 2) { r4[n] = CONV3_(pr_, 0); *(LAS f32x4*)(lw + 1024 + fr * 64 + c) = r4[n]; }
;         kk4[n] = k4[n] * *(const f32x4*)(P.k_k + col);
;         ss += (kk4[n].x * kk4[n].x + kk4[n].y * kk4[n].y) + (kk4[n].z * kk4[n].z + kk4[n].w * kk4[n].w); }
	v_pk_mul_f32 v[170:171], v[206:207], v[170:171]
	v_pk_mul_f32 v[204:205], v[204:205], v[240:241]
	v_pk_fma_f32 v[170:171], v[186:187], v[238:239], v[170:171]
	v_pk_fma_f32 v[184:185], v[184:185], v[232:233], v[204:205]
	v_lshlrev_b32_e32 v204, 16, v242
	v_and_b32_e32 v205, 0xffff0000, v242
	v_lshlrev_b32_e32 v186, 16, v237
	v_and_b32_e32 v187, 0xffff0000, v237
	s_waitcnt vmcnt(0)
	v_pk_fma_f32 v[204:205], v[210:211], v[204:205], v[170:171]
	v_lshl_add_u64 v[170:171], s[80:81], 0, v[168:169]
	v_pk_fma_f32 v[206:207], v[208:209], v[186:187], v[184:185]
	global_load_dwordx4 v[208:211], v[170:171], off
	v_add_co_u32_e64 v184, s[4:5], s26, v170
	s_nop 0
	s_nop 0
	v_addc_co_u32_e64 v185, s[4:5], 0, v171, s[4:5]
	global_load_dwordx4 v[238:241], v[184:185], off offset:2048
	v_add_co_u32_e64 v186, s[4:5], s96, v170
	v_lshlrev_b32_e32 v232, 16, v203
	s_nop 0
	v_addc_co_u32_e64 v187, s[4:5], 0, v171, s[4:5]
	global_load_dwordx4 v[242:245], v[186:187], off
	v_and_b32_e32 v233, 0xffff0000, v203
	v_and_b32_e32 v203, 0xffff0000, v166
	v_lshlrev_b32_e32 v166, 16, v167
	v_and_b32_e32 v167, 0xffff0000, v167
	s_mov_b32 s4, 0
	s_waitcnt vmcnt(1)
	v_pk_mul_f32 v[166:167], v[240:241], v[166:167]
	v_pk_mul_f32 v[202:203], v[238:239], v[202:203]
	v_pk_fma_f32 v[166:167], v[210:211], v[246:247], v[166:167]
	global_load_dwordx4 v[246:249], v[162:163], off offset:2112
	v_pk_fma_f32 v[202:203], v[208:209], v[232:233], v[202:203]
	v_lshlrev_b32_e32 v208, 16, v195
	v_and_b32_e32 v209, 0xffff0000, v195
	v_lshlrev_b32_e32 v210, 16, v193
	v_and_b32_e32 v211, 0xffff0000, v193
	s_waitcnt vmcnt(1)
	v_pk_fma_f32 v[210:211], v[244:245], v[210:211], v[166:167]
	v_pk_fma_f32 v[208:209], v[242:243], v[208:209], v[202:203]
	global_load_dwordx4 v[242:245], v[160:161], off offset:64
	s_nop 0
	global_store_dwordx4 v[176:177], v[208:211], off offset:1280
	v_cndmask_b32_e32 v233, v180, v154, vcc
	v_lshl_add_u64 v[154:155], s[72:73], 0, v[168:169]
	global_load_dwordx4 v[238:241], v[154:155], off
	ds_write_b128 v233, v[208:211] offset:768
	v_and_b32_e32 v195, 0xffff0000, v192
	s_waitcnt vmcnt(0)
	v_pk_mul_f32 v[208:209], v[204:205], v[240:241]
	v_pk_mul_f32 v[210:211], v[206:207], v[238:239]
	v_pk_mul_f32 v[166:167], v[208:209], v[208:209]
	v_pk_mul_f32 v[202:203], v[210:211], v[210:211]
	s_nop 0
	v_pk_mov_b32 v[238:239], v[202:203], v[166:167] op_sel:[1,0]
	v_mov_b32_e32 v203, v167
	v_pk_add_f32 v[166:167], v[238:239], v[202:203]
	global_load_dwordx4 v[238:241], v[158:159], off offset:2112
	v_lshlrev_b32_e32 v202, 16, v201
	v_and_b32_e32 v203, 0xffff0000, v201
	v_and_b32_e32 v201, 0xffff0000, v156
	v_lshlrev_b32_e32 v156, 16, v157
	v_and_b32_e32 v157, 0xffff0000, v157
	v_pk_mul_f32 v[156:157], v[244:245], v[156:157]
	v_pk_mul_f32 v[200:201], v[242:243], v[200:201]
	global_load_dwordx4 v[242:245], v[186:187], off offset:64
	s_waitcnt vmcnt(1)
	v_pk_fma_f32 v[156:157], v[240:241], v[250:251], v[156:157]
	v_pk_fma_f32 v[200:201], v[238:239], v[202:203], v[200:201]
	global_load_dwordx4 v[238:241], v[184:185], off offset:2112
	v_lshlrev_b32_e32 v202, 16, v194
	v_and_b32_e32 v203, 0xffff0000, v194
	v_lshlrev_b32_e32 v194, 16, v192
	v_pk_fma_f32 v[192:193], v[248:249], v[194:195], v[156:157]
	global_load_dwordx4 v[248:251], v[170:171], off offset:64
	v_pk_fma_f32 v[194:195], v[246:247], v[202:203], v[200:201]
	v_lshlrev_b32_e32 v156, 16, v189
	v_and_b32_e32 v157, 0xffff0000, v189
	v_lshlrev_b32_e32 v246, 16, v188
	v_and_b32_e32 v247, 0xffff0000, v188
	v_lshlrev_b32_e32 v188, 16, v254
	v_and_b32_e32 v189, 0xffff0000, v254
	v_lshlrev_b32_e32 v144, 16, v255
	v_and_b32_e32 v145, 0xffff0000, v255
	s_waitcnt vmcnt(1)
	v_pk_mul_f32 v[144:145], v[240:241], v[144:145]
	v_pk_mul_f32 v[188:189], v[238:239], v[188:189]
	global_load_dwordx4 v[238:241], v[154:155], off offset:64
	s_waitcnt vmcnt(1)
	v_pk_fma_f32 v[144:145], v[250:251], v[246:247], v[144:145]
	v_pk_fma_f32 v[156:157], v[248:249], v[156:157], v[188:189]
	global_load_dwordx4 v[246:249], v[162:163], off offset:2176
	v_lshlrev_b32_e32 v188, 16, v179
	v_and_b32_e32 v189, 0xffff0000, v179
	v_lshlrev_b32_e32 v200, 16, v178
	v_and_b32_e32 v201, 0xffff0000, v178
	v_pk_fma_f32 v[202:203], v[244:245], v[200:201], v[144:145]
	v_pk_fma_f32 v[200:201], v[242:243], v[188:189], v[156:157]
	global_load_dwordx4 v[242:245], v[160:161], off offset:128
	s_nop 0
	global_store_dwordx4 v[176:177], v[200:203], off offset:1344
	s_nop 0
	v_add_u32_e32 v144, 0x2040, v234
	v_cndmask_b32_e32 v232, v180, v144, vcc
	ds_write_b128 v232, v[200:203] offset:768
	s_waitcnt vmcnt(3)
	v_pk_mul_f32 v[200:201], v[192:193], v[240:241]
	v_pk_mul_f32 v[202:203], v[194:195], v[238:239]
	global_load_dwordx4 v[238:241], v[158:159], off offset:2176
	s_nop 0
	s_nop 0
	v_pk_mul_f32 v[144:145], v[200:201], v[200:201]
	v_pk_mul_f32 v[156:157], v[202:203], v[202:203]
	s_nop 0
	v_pk_mov_b32 v[178:179], v[156:157], v[144:145] op_sel:[1,0]
	v_mov_b32_e32 v157, v145
	v_pk_add_f32 v[250:251], v[178:179], v[156:157]
	v_lshlrev_b32_e32 v178, 16, v148
	v_and_b32_e32 v179, 0xffff0000, v148
	v_lshlrev_b32_e32 v148, 16, v149
	v_and_b32_e32 v149, 0xffff0000, v149
	v_lshlrev_b32_e32 v144, 16, v199
	v_and_b32_e32 v145, 0xffff0000, v199
	v_lshlrev_b32_e32 v156, 16, v198
	v_and_b32_e32 v157, 0xffff0000, v198
	s_waitcnt vmcnt(2)
	v_pk_mul_f32 v[148:149], v[244:245], v[148:149]
	v_pk_mul_f32 v[178:179], v[242:243], v[178:179]
	global_load_dwordx4 v[242:245], v[184:185], off offset:2176
	s_waitcnt vmcnt(1)
; #define LAS __attribute__((address_space(3)))
; __device__ __forceinline__ float shx(float v, int o, int lane) { return __builtin_bit_cast(float, __builtin_amdgcn_ds_bpermute((lane ^ o) << 2, __builtin_bit_cast(int, v))); }
; #define lane LANE_()
; template <int MODE>
; __device__ __forceinline__ void scan_prologue(const ScanP& P, int m0, int seqbase, int T, int h, int d, float* slab, LAS float* lw, float* bon, int lane) {
;     ...
;     for (int n = 0; n < 4; ++n) { const int c = 16 * n + 4 * fq, col = h * 64 + c;
;         k4[n] = CONV3_(pk_, 1);
;         if (MODE != 1) { const f32x4 v4 = CONV3_(pv_, 2); *(f32x4*)(srow + 320 + c) = v4; LAS float* xsel = (fr == (d ? 15 : 0)) ? lw + 2048 + c : lw + 2304 + lane * 4; *(LAS f32x4*)(xsel + 192) = v4; }
;         if (MODE == 2) { r4[n] = CONV3_(pr_, 0); *(LAS f32x4*)(lw + 1024 + fr * 64 + c) = r4[n]; }
;         kk4[n] = k4[n] * *(const f32x4*)(P.k_k + col);
;         ss += (kk4[n].x * kk4[n].x + kk4[n].y * kk4[n].y) + (kk4[n].z * kk4[n].z + kk4[n].w * kk4[n].w); }
;     ...
;     ss += shx(ss, 16, lane); ss += shx(ss, 32, lane);
	v_pk_fma_f32 v[148:149], v[240:241], v[156:157], v[148:149]
	v_pk_fma_f32 v[144:145], v[238:239], v[144:145], v[178:179]
	global_load_dwordx4 v[238:241], v[170:171], off offset:128
	v_lshlrev_b32_e32 v156, 16, v191
	v_and_b32_e32 v157, 0xffff0000, v191
	v_lshlrev_b32_e32 v178, 16, v190
	v_and_b32_e32 v179, 0xffff0000, v190
	v_pk_fma_f32 v[188:189], v[248:249], v[178:179], v[148:149]
	v_pk_fma_f32 v[190:191], v[246:247], v[156:157], v[144:145]
	global_load_dwordx4 v[246:249], v[186:187], off offset:128
	v_lshlrev_b32_e32 v156, 16, v146
	v_and_b32_e32 v157, 0xffff0000, v146
	v_lshlrev_b32_e32 v146, 16, v147
	v_and_b32_e32 v147, 0xffff0000, v147
	v_lshlrev_b32_e32 v144, 16, v197
	v_and_b32_e32 v145, 0xffff0000, v197
	v_lshlrev_b32_e32 v148, 16, v196
	v_and_b32_e32 v149, 0xffff0000, v196
	v_lshlrev_b32_e32 v178, 16, v213
	v_and_b32_e32 v179, 0xffff0000, v213
	s_waitcnt vmcnt(2)
	v_pk_mul_f32 v[146:147], v[244:245], v[146:147]
	v_pk_mul_f32 v[156:157], v[242:243], v[156:157]
	global_load_dwordx4 v[242:245], v[154:155], off offset:128
	s_waitcnt vmcnt(2)
	v_pk_fma_f32 v[146:147], v[240:241], v[148:149], v[146:147]
	v_pk_fma_f32 v[144:145], v[238:239], v[144:145], v[156:157]
	global_load_dwordx4 v[238:241], v[158:159], off offset:2240
	v_lshlrev_b32_e32 v148, 16, v183
	v_and_b32_e32 v149, 0xffff0000, v183
	v_lshlrev_b32_e32 v156, 16, v182
	v_and_b32_e32 v157, 0xffff0000, v182
	s_waitcnt vmcnt(2)
	v_pk_fma_f32 v[146:147], v[248:249], v[156:157], v[146:147]
	v_pk_fma_f32 v[144:145], v[246:247], v[148:149], v[144:145]
	global_load_dwordx4 v[246:249], v[160:161], off offset:192
	v_add_u32_e32 v148, 0x2080, v234
	global_store_dwordx4 v[176:177], v[144:147], off offset:1408
	v_cndmask_b32_e32 v230, v180, v148, vcc
	ds_write_b128 v230, v[144:147] offset:768
	s_nop 0
	v_lshlrev_b32_e32 v182, 16, v150
	v_and_b32_e32 v183, 0xffff0000, v150
	v_lshlrev_b32_e32 v150, 16, v151
	v_and_b32_e32 v151, 0xffff0000, v151
	v_lshlrev_b32_e32 v148, 16, v214
	v_and_b32_e32 v149, 0xffff0000, v214
	s_waitcnt vmcnt(3)
	v_pk_mul_f32 v[196:197], v[188:189], v[244:245]
	v_pk_mul_f32 v[198:199], v[190:191], v[242:243]
	global_load_dwordx4 v[242:245], v[162:163], off offset:2240
	s_nop 0
	s_nop 0
	s_nop 0
	s_nop 0
	s_nop 0
	s_waitcnt vmcnt(2)
	v_pk_mul_f32 v[150:151], v[248:249], v[150:151]
	v_pk_mul_f32 v[156:157], v[246:247], v[182:183]
	global_load_dwordx4 v[246:249], v[170:171], off offset:192
	v_pk_fma_f32 v[146:147], v[240:241], v[178:179], v[150:151]
	v_pk_fma_f32 v[144:145], v[238:239], v[148:149], v[156:157]
	global_load_dwordx4 v[238:241], v[184:185], off offset:2240
	global_load_dwordx4 v[156:159], v[186:187], off offset:192
	v_lshlrev_b32_e32 v148, 16, v216
	v_and_b32_e32 v149, 0xffff0000, v216
	v_lshlrev_b32_e32 v150, 16, v215
	v_and_b32_e32 v151, 0xffff0000, v215
	s_waitcnt vmcnt(3)
	v_pk_fma_f32 v[178:179], v[244:245], v[150:151], v[146:147]
	v_pk_fma_f32 v[182:183], v[242:243], v[148:149], v[144:145]
	global_load_dwordx4 v[242:245], v[154:155], off offset:192
	v_lshlrev_b32_e32 v170, 16, v152
	v_and_b32_e32 v171, 0xffff0000, v152
	v_lshlrev_b32_e32 v152, 16, v153
	v_and_b32_e32 v153, 0xffff0000, v153
	v_lshlrev_b32_e32 v160, 16, v229
	v_and_b32_e32 v161, 0xffff0000, v229
	v_lshlrev_b32_e32 v162, 16, v217
	v_and_b32_e32 v163, 0xffff0000, v217
	s_waitcnt vmcnt(2)
	v_pk_mul_f32 v[150:151], v[240:241], v[152:153]
	v_pk_mul_f32 v[148:149], v[238:239], v[170:171]
	v_pk_fma_f32 v[146:147], v[248:249], v[162:163], v[150:151]
	v_pk_fma_f32 v[144:145], v[246:247], v[160:161], v[148:149]
	v_lshlrev_b32_e32 v148, 16, v236
	v_and_b32_e32 v149, 0xffff0000, v236
	v_lshlrev_b32_e32 v150, 16, v235
	v_and_b32_e32 v151, 0xffff0000, v235
	s_waitcnt vmcnt(1)
	v_pk_fma_f32 v[146:147], v[158:159], v[150:151], v[146:147]
	v_pk_fma_f32 v[144:145], v[156:157], v[148:149], v[144:145]
	v_add_u32_e32 v148, 0x20c0, v234
	global_store_dwordx4 v[176:177], v[144:147], off offset:1472
	v_cndmask_b32_e32 v229, v180, v148, vcc
	ds_write_b128 v229, v[144:147] offset:768
	s_nop 0
	v_lshl_or_b32 v180, v231, 6, s89
	s_waitcnt vmcnt(1)
	v_pk_mul_f32 v[186:187], v[182:183], v[242:243]
	v_pk_mul_f32 v[184:185], v[178:179], v[244:245]
	v_mul_f32_e32 v146, v186, v186
	v_pk_add_f32 v[144:145], v[166:167], v[166:167] op_sel:[0,1] op_sel_hi:[1,0]
	v_mul_f32_e32 v148, v187, v187
	v_mov_b32_e32 v145, v146
	v_pk_add_f32 v[146:147], v[250:251], v[250:251] op_sel:[0,1] op_sel_hi:[1,0]
	v_mul_f32_e32 v149, v184, v184
	v_mov_b32_e32 v147, v148
	v_pk_add_f32 v[144:145], v[144:145], v[146:147]
	v_mul_f32_e32 v146, v199, v199
	v_pk_fma_f32 v[146:147], v[198:199], v[198:199], v[146:147] op_sel_hi:[1,1,0]
	v_mul_f32_e32 v148, v197, v197
	v_mul_f32_e32 v150, v185, v185
	v_mov_b32_e32 v147, v149
	v_pk_fma_f32 v[148:149], v[196:197], v[196:197], v[148:149] op_sel_hi:[1,1,0]
	s_nop 0
	v_mov_b32_e32 v149, v150
	v_pk_add_f32 v[146:147], v[146:147], v[148:149]
	s_nop 0
	v_pk_add_f32 v[144:145], v[144:145], v[146:147]
	s_nop 0
	v_add_f32_e32 v144, v144, v145
	v_lshlrev_b32_e32 v145, 2, v212
	v_xor_b32_e32 v146, 64, v145
	ds_bpermute_b32 v146, v146, v144
	v_xor_b32_e32 v145, 0x80, v145
	s_waitcnt lgkmcnt(0)
	v_add_f32_e32 v144, v144, v146
	ds_bpermute_b32 v145, v145, v144
	s_waitcnt lgkmcnt(0)
; __device__ __forceinline__ unsigned pk2(float lo, float hi) { const f2 v = {lo, hi}; return __builtin_bit_cast(unsigned, __builtin_convertvector(v, bf16x2_hw)); }
; __device__ __forceinline__ float tanhf_(float x) { return 1.0f - 2.0f * __builtin_amdgcn_rcpf(1.0f + __builtin_amdgcn_exp2f(2.8853900817779268f * x)); }
; __device__ __forceinline__ float shx(float v, int o, int lane) { return __builtin_bit_cast(float, __builtin_amdgcn_ds_bpermute((lane ^ o) << 2, __builtin_bit_cast(int, v))); }
; #define lane LANE_()
; template <int MODE>
; __device__ __forceinline__ void scan_prologue(const ScanP& P, int m0, int seqbase, int T, int h, int d, float* slab, LAS float* lw, float* bon, int lane) {
;     ...
;     ss += shx(ss, 16, lane); ss += shx(ss, 32, lane);
;     const float rs = __builtin_amdgcn_rsqf(ss + 1e-12f);
;     f32x4 Dw[4], Da[4];
; #pragma unroll
;     for (int n = 0; n < 4; ++n) { Dw[n] = (f32x4){0.f, 0.f, 0.f, 0.f}; Da[n] = (f32x4){0.f, 0.f, 0.f, 0.f}; }
; #pragma unroll
;     for (int ks = 0; ks < 2; ++ks) {
;         const v4u xw = xw_[ks]; const bf16x8 xa = xa_[ks];
;         v4u tw;
; #pragma unroll
;         for (int e = 0; e < 4; ++e) tw[e] = pk2(tanhf_(bflo(xw[e])), tanhf_(bfhi(xw[e])));
;         const bf16x8 twv = __builtin_bit_cast(bf16x8, tw);
; #pragma unroll
;         for (int n = 0; n < 4; ++n) { const size_t wo = (size_t)(h * 64 + 16 * n + fr) * 64 + ks * 32 + 8 * fq;
;             Dw[n] = __builtin_amdgcn_mfma_f32_16x16x32_bf16(*(const bf16x8*)(P.upw + wo), twv, Dw[n], 0, 0, 0);
;             Da[n] = __builtin_amdgcn_mfma_f32_16x16x32_bf16(*(const bf16x8*)(P.upa + wo), xa, Da[n], 0, 0, 0); }
;     }
	v_add_f32_e32 v144, v144, v145
	v_add_f32_e32 v212, 0x2b8cbccc, v144
	v_lshlrev_b32_e32 v144, 16, v140
	v_and_b32_e32 v140, 0xffff0000, v140
	v_mul_f32_e32 v140, 0x4038aa3b, v140
	v_exp_f32_e32 v140, v140
	v_mul_f32_e32 v144, 0x4038aa3b, v144
	v_exp_f32_e32 v144, v144
	v_add_f32_e32 v140, 1.0, v140
	v_rcp_f32_e32 v145, v140
	v_lshlrev_b32_e32 v140, 16, v141
	v_and_b32_e32 v141, 0xffff0000, v141
	v_mul_f32_e32 v140, 0x4038aa3b, v140
	v_mul_f32_e32 v141, 0x4038aa3b, v141
	v_exp_f32_e32 v140, v140
	v_exp_f32_e32 v141, v141
	v_add_f32_e32 v144, 1.0, v144
	v_rcp_f32_e32 v144, v144
	v_add_f32_e32 v140, 1.0, v140
	v_add_f32_e32 v141, 1.0, v141
	v_rcp_f32_e32 v140, v140
	v_rcp_f32_e32 v141, v141
	v_pk_fma_f32 v[144:145], v[144:145], 2.0, 1.0 op_sel_hi:[1,0,0] neg_lo:[1,0,0] neg_hi:[1,0,0]
	v_pk_fma_f32 v[140:141], v[140:141], 2.0, 1.0 op_sel_hi:[1,0,0] neg_lo:[1,0,0] neg_hi:[1,0,0]
	s_nop 0
	v_cvt_pk_bf16_f32 v153, v140, v141
	v_lshlrev_b32_e32 v140, 16, v142
	v_and_b32_e32 v141, 0xffff0000, v142
	v_mul_f32_e32 v140, 0x4038aa3b, v140
	v_mul_f32_e32 v141, 0x4038aa3b, v141
	v_exp_f32_e32 v140, v140
	v_exp_f32_e32 v141, v141
	v_cvt_pk_bf16_f32 v152, v144, v145
	v_add_f32_e32 v140, 1.0, v140
	v_add_f32_e32 v141, 1.0, v141
	v_rcp_f32_e32 v140, v140
	v_rcp_f32_e32 v141, v141
	s_nop 0
	v_pk_fma_f32 v[140:141], v[140:141], 2.0, 1.0 op_sel_hi:[1,0,0] neg_lo:[1,0,0] neg_hi:[1,0,0]
	s_nop 0
	v_cvt_pk_bf16_f32 v154, v140, v141
	v_lshlrev_b32_e32 v140, 16, v143
	v_and_b32_e32 v141, 0xffff0000, v143
	v_mul_f32_e32 v140, 0x4038aa3b, v140
	v_mul_f32_e32 v141, 0x4038aa3b, v141
	v_exp_f32_e32 v140, v140
	v_exp_f32_e32 v141, v141
	v_add_f32_e32 v140, 1.0, v140
	v_add_f32_e32 v141, 1.0, v141
	v_rcp_f32_e32 v140, v140
	v_rcp_f32_e32 v141, v141
	s_nop 0
	v_pk_fma_f32 v[140:141], v[140:141], 2.0, 1.0 op_sel_hi:[1,0,0] neg_lo:[1,0,0] neg_hi:[1,0,0]
	s_nop 0
	v_cvt_pk_bf16_f32 v155, v140, v141
	v_lshl_add_u64 v[140:141], v[180:181], 0, v[164:165]
	v_lshlrev_b64 v[144:145], 1, v[140:141]
	v_lshl_add_u64 v[170:171], s[78:79], 0, v[144:145]
	global_load_dwordx4 v[246:249], v[170:171], off
	global_load_dwordx4 v[156:159], v[170:171], off offset:2048
	s_waitcnt vmcnt(0)
	v_mfma_f32_16x16x32_bf16 v[160:163], v[156:159], v[136:139], 0
	v_or_b32_e32 v156, 0x800, v180
	v_mov_b32_e32 v157, v181
	v_lshl_add_u64 v[156:157], v[156:157], 0, v[164:165]
	v_lshlrev_b64 v[236:237], 1, v[156:157]
	v_lshl_add_u64 v[166:167], s[74:75], 0, v[144:145]
	global_load_dwordx4 v[140:143], v[166:167], off
	global_load_dwordx4 v[148:151], v[166:167], off offset:2048
	v_lshl_add_u64 v[156:157], s[74:75], 0, v[236:237]
	global_load_dwordx4 v[144:147], v[156:157], off
	s_nop 0
	s_nop 0
	s_nop 0
	s_nop 0
	s_nop 0
	s_waitcnt vmcnt(0)
	v_mfma_f32_16x16x32_bf16 v[214:217], v[144:147], v[152:155], 0
	v_lshl_add_u64 v[156:157], s[78:79], 0, v[236:237]
	global_load_dwordx4 v[156:159], v[156:157], off
	s_waitcnt vmcnt(0)
	v_mfma_f32_16x16x32_bf16 v[236:239], v[156:159], v[136:139], 0
	v_or_b32_e32 v156, 0xc00, v180
	v_mov_b32_e32 v157, v181
	v_lshl_add_u64 v[156:157], v[156:157], 0, v[164:165]
	v_lshlrev_b64 v[244:245], 1, v[156:157]
	v_lshl_add_u64 v[156:157], s[74:75], 0, v[244:245]
	global_load_dwordx4 v[156:159], v[156:157], off
	v_mfma_f32_16x16x32_bf16 v[140:143], v[140:143], v[152:155], 0
	v_mfma_f32_16x16x32_bf16 v[148:151], v[148:151], v[152:155], 0
	s_waitcnt vmcnt(0)
	v_mfma_f32_16x16x32_bf16 v[240:243], v[156:159], v[152:155], 0
	global_load_dwordx4 v[156:159], v[166:167], off offset:64
	v_lshl_add_u64 v[152:153], s[78:79], 0, v[244:245]
	global_load_dwordx4 v[152:155], v[152:153], off
	v_mfma_f32_16x16x32_bf16 v[144:147], v[246:249], v[136:139], 0
	global_load_dwordx4 v[248:251], v[170:171], off offset:64
	s_waitcnt vmcnt(1)
	v_mfma_f32_16x16x32_bf16 v[244:247], v[152:155], v[136:139], 0
	v_lshlrev_b32_e32 v136, 16, v128
	v_and_b32_e32 v128, 0xffff0000, v128
	v_mul_f32_e32 v136, 0x4038aa3b, v136
	v_mul_f32_e32 v128, 0x4038aa3b, v128
	v_exp_f32_e32 v136, v136
	v_exp_f32_e32 v128, v128
	v_add_f32_e32 v136, 1.0, v136
	v_add_f32_e32 v128, 1.0, v128
	v_rcp_f32_e32 v136, v136
	v_rcp_f32_e32 v137, v128
	s_nop 0
	v_pk_fma_f32 v[136:137], v[136:137], 2.0, 1.0 op_sel_hi:[1,0,0] neg_lo:[1,0,0] neg_hi:[1,0,0]
	s_nop 0
	v_cvt_pk_bf16_f32 v128, v136, v137
	v_lshlrev_b32_e32 v136, 16, v129
	v_and_b32_e32 v129, 0xffff0000, v129
	v_mul_f32_e32 v136, 0x4038aa3b, v136
	v_mul_f32_e32 v129, 0x4038aa3b, v129
	v_exp_f32_e32 v136, v136
	v_exp_f32_e32 v129, v129
	v_add_f32_e32 v136, 1.0, v136
	v_add_f32_e32 v129, 1.0, v129
	v_rcp_f32_e32 v136, v136
	v_rcp_f32_e32 v137, v129
	s_nop 0
	v_pk_fma_f32 v[136:137], v[136:137], 2.0, 1.0 op_sel_hi:[1,0,0] neg_lo:[1,0,0] neg_hi:[1,0,0]
	s_nop 0
	v_cvt_pk_bf16_f32 v129, v136, v137
	v_lshlrev_b32_e32 v136, 16, v130
	v_and_b32_e32 v130, 0xffff0000, v130
	v_mul_f32_e32 v136, 0x4038aa3b, v136
	v_mul_f32_e32 v130, 0x4038aa3b, v130
	v_exp_f32_e32 v136, v136
	v_exp_f32_e32 v130, v130
	v_add_f32_e32 v136, 1.0, v136
	v_add_f32_e32 v130, 1.0, v130
	v_rcp_f32_e32 v136, v136
	v_rcp_f32_e32 v137, v130
	s_nop 0
	v_pk_fma_f32 v[136:137], v[136:137], 2.0, 1.0 op_sel_hi:[1,0,0] neg_lo:[1,0,0] neg_hi:[1,0,0]
	s_nop 0
	v_cvt_pk_bf16_f32 v130, v136, v137
	v_lshlrev_b32_e32 v136, 16, v131
	v_and_b32_e32 v131, 0xffff0000, v131
	v_mul_f32_e32 v136, 0x4038aa3b, v136
	v_mul_f32_e32 v131, 0x4038aa3b, v131
	v_exp_f32_e32 v136, v136
	v_exp_f32_e32 v131, v131
	v_add_f32_e32 v136, 1.0, v136
	v_add_f32_e32 v131, 1.0, v131
	v_rcp_f32_e32 v136, v136
	v_rcp_f32_e32 v137, v131
	s_nop 0
	v_pk_fma_f32 v[136:137], v[136:137], 2.0, 1.0 op_sel_hi:[1,0,0] neg_lo:[1,0,0] neg_hi:[1,0,0]
	s_nop 0
	v_cvt_pk_bf16_f32 v131, v136, v137
	global_load_dwordx4 v[136:139], v[166:167], off offset:2112
	s_nop 0
	v_mfma_f32_16x16x32_bf16 v[152:155], v[156:159], v[128:131], v[140:143]
	global_load_dwordx4 v[140:143], v[170:171], off offset:2112
	s_nop 0
	s_waitcnt vmcnt(2)
; #define LAS __attribute__((address_space(3)))
; __device__ __forceinline__ float sigmoidf_(float x) { return __builtin_amdgcn_rcpf(1.0f + __builtin_amdgcn_exp2f(-1.4426950408889634f * x)); }
; #define lane LANE_()
; template <int MODE>
; __device__ __forceinline__ void scan_prologue(const ScanP& P, int m0, int seqbase, int T, int h, int d, float* slab, LAS float* lw, float* bon, int lane) {
;     ...
;         for (int n = 0; n < 4; ++n) { const size_t wo = (size_t)(h * 64 + 16 * n + fr) * 64 + ks * 32 + 8 * fq;
;             Dw[n] = __builtin_amdgcn_mfma_f32_16x16x32_bf16(*(const bf16x8*)(P.upw + wo), twv, Dw[n], 0, 0, 0);
;             Da[n] = __builtin_amdgcn_mfma_f32_16x16x32_bf16(*(const bf16x8*)(P.upa + wo), xa, Da[n], 0, 0, 0); }
;     }
;     float bp = 0.f;
; #pragma unroll
;     for (int n = 0; n < 4; ++n) { const int c = 16 * n + 4 * fq, col = h * 64 + c;
;         const f32x4 w0 = *(const f32x4*)(P.w0 + col), a0 = *(const f32x4*)(P.a0 + col), ka = *(const f32x4*)(P.k_a + col);
;         f32x4 wv, bv, kd, av;
; #pragma unroll
;         for (int i = 0; i < 4; ++i) { const float ic = sigmoidf_(Da[n][i] + a0[i]);
;             wv[i] = __builtin_amdgcn_exp2f(-DECAY_SCALE * 1.4426950408889634f * sigmoidf_(Dw[n][i] + w0[i]));
;             const float kk = kk4[n][i] * rs; av[i] = -kk; bv[i] = kk * ic; kd[i] = k4[n][i] * (1.0f + (ic - 1.0f) * ka[i]); }
;         *(LAS f32x4*)(lw + fr * 64 + c) = av; *(LAS f32x4*)(lw + 3072 + fr * 64 + c) = wv; *(LAS f32x4*)(lw + (MODE == 3 ? 1024 : 4096) + fr * 64 + c) = bv;
;         if (MODE != 1) *(f32x4*)(srow + 192 + c) = kd;
;         { LAS float* xsel = (fr == (d ? 15 : 0)) ? lw + 2048 + c : lw + 2304 + lane * 4;
;           if (MODE != 1) *(LAS f32x4*)(xsel + 128) = kd; }
;         if (MODE == 2) { const f32x4 rk = *(const f32x4*)(P.r_k + col); const f32x4 t = r4[n] * kd * rk; bp += (t.x + t.y) + (t.z + t.w); }
;         if ((n & 1) == 1) asm volatile("" ::: "memory");
;     }
	v_mfma_f32_16x16x32_bf16 v[156:159], v[248:251], v[132:135], v[144:147]
	s_nop 0
	s_waitcnt vmcnt(1)
	v_mfma_f32_16x16x32_bf16 v[144:147], v[136:139], v[128:131], v[148:151]
	s_nop 0
	s_waitcnt vmcnt(0)
	v_mfma_f32_16x16x32_bf16 v[148:151], v[140:143], v[132:135], v[160:163]
	v_or_b32_e32 v136, 0x820, v180
	v_mov_b32_e32 v137, v181
	v_or_b32_e32 v180, 0xc20, v180
	v_lshl_add_u64 v[136:137], v[136:137], 0, v[164:165]
	v_lshl_add_u64 v[160:161], v[180:181], 0, v[164:165]
	v_lshlrev_b64 v[140:141], 1, v[136:137]
	v_lshlrev_b64 v[164:165], 1, v[160:161]
	v_lshl_add_u64 v[136:137], s[74:75], 0, v[140:141]
	global_load_dwordx4 v[248:251], v[136:137], off
	v_lshl_add_u64 v[160:161], s[74:75], 0, v[164:165]
	s_nop 0
	v_lshl_add_u64 v[140:141], s[78:79], 0, v[140:141]
	global_load_dwordx4 v[160:163], v[160:161], off
	v_rsq_f32_e32 v180, v212
	global_load_dwordx4 v[140:143], v[140:141], off
	s_waitcnt vmcnt(2)
	v_mfma_f32_16x16x32_bf16 v[136:139], v[248:251], v[128:131], v[214:217]
	s_nop 2
	v_lshl_add_u64 v[214:215], s[76:77], 0, v[168:169]
	global_load_dwordx4 v[248:251], v[214:215], off
	v_lshl_add_u64 v[212:213], s[10:11], 0, v[168:169]
	v_lshl_add_u64 v[216:217], s[6:7], 0, v[168:169]
	global_load_dwordx4 v[168:171], v[216:217], off
	s_waitcnt vmcnt(3)
	v_mfma_f32_16x16x32_bf16 v[128:131], v[160:163], v[128:131], v[240:243]
	global_load_dwordx4 v[240:243], v[212:213], off
	v_lshl_add_u64 v[160:161], s[78:79], 0, v[164:165]
	global_load_dwordx4 v[160:163], v[160:161], off
	s_nop 0
	s_nop 0
	s_waitcnt vmcnt(4)
	v_mfma_f32_16x16x32_bf16 v[140:143], v[140:143], v[132:135], v[236:239]
	global_load_dwordx4 v[236:239], v[216:217], off offset:64
	s_nop 0
	s_waitcnt vmcnt(4)
	v_add_f32_e32 v156, v156, v248
	s_waitcnt vmcnt(1)
	v_mfma_f32_16x16x32_bf16 v[132:135], v[160:163], v[132:135], v[244:247]
	global_load_dwordx4 v[244:247], v[214:215], off offset:64
	s_nop 0
	v_add_f32_e32 v158, v158, v250
	v_mul_f32_e32 v156, 0xbfb8aa3b, v156
	v_mul_f32_e32 v158, 0xbfb8aa3b, v158
	v_exp_f32_e32 v156, v156
	v_exp_f32_e32 v158, v158
	v_add_f32_e32 v156, 1.0, v156
	v_add_f32_e32 v158, 1.0, v158
	v_rcp_f32_e32 v164, v156
	v_add_f32_e32 v156, v157, v249
	v_rcp_f32_e32 v166, v158
	v_add_f32_e32 v158, v159, v251
	global_load_dwordx4 v[248:251], v[212:213], off offset:64
	v_mul_f32_e32 v156, 0xbfb8aa3b, v156
	v_mul_f32_e32 v158, 0xbfb8aa3b, v158
	v_exp_f32_e32 v156, v156
	v_exp_f32_e32 v158, v158
	v_add_f32_e32 v156, 1.0, v156
	v_add_f32_e32 v158, 1.0, v158
	v_rcp_f32_e32 v165, v156
	v_rcp_f32_e32 v167, v158
	v_add_f32_e32 v152, v152, v240
	v_add_f32_e32 v153, v153, v241
	v_add_f32_e32 v154, v154, v242
	v_add_f32_e32 v155, v155, v243
	global_load_dwordx4 v[240:243], v[212:213], off offset:128
	v_mul_f32_e32 v152, 0xbfb8aa3b, v152
	v_mul_f32_e32 v153, 0xbfb8aa3b, v153
	v_mul_f32_e32 v154, 0xbfb8aa3b, v154
	v_mul_f32_e32 v155, 0xbfb8aa3b, v155
	v_exp_f32_e32 v152, v152
	v_exp_f32_e32 v153, v153
	v_exp_f32_e32 v154, v154
	v_exp_f32_e32 v155, v155
	v_add_f32_e32 v152, 1.0, v152
	v_add_f32_e32 v153, 1.0, v153
	v_add_f32_e32 v154, 1.0, v154
	v_add_f32_e32 v155, 1.0, v155
	v_rcp_f32_e32 v152, v152
	v_rcp_f32_e32 v153, v153
	v_rcp_f32_e32 v154, v154
	v_rcp_f32_e32 v155, v155
	v_mul_f32_e32 v152, 0xbf60028a, v152
	v_mul_f32_e32 v153, 0xbf60028a, v153
	v_pk_mul_f32 v[160:161], v[210:211], v[180:181] op_sel_hi:[1,0]
	v_mul_f32_e32 v154, 0xbf60028a, v154
	v_mul_f32_e32 v155, 0xbf60028a, v155
	v_pk_mul_f32 v[162:163], v[208:209], v[180:181] op_sel_hi:[1,0]
	global_load_dwordx4 v[208:211], v[214:215], off offset:128
	v_exp_f32_e32 v152, v152
	v_exp_f32_e32 v153, v153
	v_xor_b32_e32 v157, 0x80000000, v161
	v_xor_b32_e32 v156, 0x80000000, v160
	v_exp_f32_e32 v154, v154
	v_exp_f32_e32 v155, v155
	v_xor_b32_e32 v158, 0x80000000, v162
	v_xor_b32_e32 v159, 0x80000000, v163
	v_pk_mul_f32 v[160:161], v[160:161], v[164:165]
	v_pk_mul_f32 v[162:163], v[162:163], v[166:167]
	v_pk_add_f32 v[166:167], v[166:167], -1.0 op_sel_hi:[1,0]
	v_pk_add_f32 v[164:165], v[164:165], -1.0 op_sel_hi:[1,0]
	v_pk_fma_f32 v[166:167], v[170:171], v[166:167], 1.0 op_sel_hi:[1,1,0]
	v_pk_fma_f32 v[164:165], v[168:169], v[164:165], 1.0 op_sel_hi:[1,1,0]
	v_pk_mul_f32 v[168:169], v[204:205], v[166:167]
	v_pk_mul_f32 v[166:167], v[206:207], v[164:165]
	global_load_dwordx4 v[204:207], v[216:217], off offset:128
	v_lshl_add_u32 v164, v231, 8, v234
	ds_write_b128 v164, v[156:159]
	ds_write_b128 v164, v[152:155] offset:12288
	ds_write_b128 v164, v[160:163] offset:4096
	global_store_dwordx4 v[176:177], v[166:169], off offset:768
	ds_write_b128 v233, v[166:169] offset:512
	global_load_dwordx4 v[166:169], v[216:217], off offset:192
	s_nop 0
	s_nop 0
	s_nop 0
	s_waitcnt vmcnt(6)
	v_add_f32_e32 v148, v148, v244
	s_waitcnt vmcnt(5)
; #define LAS __attribute__((address_space(3)))
; __device__ __forceinline__ float sigmoidf_(float x) { return __builtin_amdgcn_rcpf(1.0f + __builtin_amdgcn_exp2f(-1.4426950408889634f * x)); }
; #define lane LANE_()
; template <int MODE>
; __device__ __forceinline__ void scan_prologue(const ScanP& P, int m0, int seqbase, int T, int h, int d, float* slab, LAS float* lw, float* bon, int lane) {
;     ...
;     for (int n = 0; n < 4; ++n) { const int c = 16 * n + 4 * fq, col = h * 64 + c;
;         const f32x4 w0 = *(const f32x4*)(P.w0 + col), a0 = *(const f32x4*)(P.a0 + col), ka = *(const f32x4*)(P.k_a + col);
;         f32x4 wv, bv, kd, av;
; #pragma unroll
;         for (int i = 0; i < 4; ++i) { const float ic = sigmoidf_(Da[n][i] + a0[i]);
;             wv[i] = __builtin_amdgcn_exp2f(-DECAY_SCALE * 1.4426950408889634f * sigmoidf_(Dw[n][i] + w0[i]));
;             const float kk = kk4[n][i] * rs; av[i] = -kk; bv[i] = kk * ic; kd[i] = k4[n][i] * (1.0f + (ic - 1.0f) * ka[i]); }
;         *(LAS f32x4*)(lw + fr * 64 + c) = av; *(LAS f32x4*)(lw + 3072 + fr * 64 + c) = wv; *(LAS f32x4*)(lw + (MODE == 3 ? 1024 : 4096) + fr * 64 + c) = bv;
;         if (MODE != 1) *(f32x4*)(srow + 192 + c) = kd;
;         { LAS float* xsel = (fr == (d ? 15 : 0)) ? lw + 2048 + c : lw + 2304 + lane * 4;
;           if (MODE != 1) *(LAS f32x4*)(xsel + 128) = kd; }
;         if (MODE == 2) { const f32x4 rk = *(const f32x4*)(P.r_k + col); const f32x4 t = r4[n] * kd * rk; bp += (t.x + t.y) + (t.z + t.w); }
;         if ((n & 1) == 1) asm volatile("" ::: "memory");
	v_add_f32_e32 v144, v144, v248
	v_add_f32_e32 v145, v145, v249
	v_add_f32_e32 v146, v146, v250
	v_add_f32_e32 v147, v147, v251
	global_load_dwordx4 v[248:251], v[214:215], off offset:192
	v_mul_f32_e32 v144, 0xbfb8aa3b, v144
	v_add_f32_e32 v149, v149, v245
	v_mul_f32_e32 v145, 0xbfb8aa3b, v145
	v_add_f32_e32 v150, v150, v246
	v_mul_f32_e32 v146, 0xbfb8aa3b, v146
	v_add_f32_e32 v151, v151, v247
	global_load_dwordx4 v[244:247], v[212:213], off offset:192
	v_mul_f32_e32 v147, 0xbfb8aa3b, v147
	v_mul_f32_e32 v148, 0xbfb8aa3b, v148
	v_exp_f32_e32 v144, v144
	v_mul_f32_e32 v149, 0xbfb8aa3b, v149
	v_exp_f32_e32 v145, v145
	v_mul_f32_e32 v150, 0xbfb8aa3b, v150
	v_exp_f32_e32 v146, v146
	v_mul_f32_e32 v151, 0xbfb8aa3b, v151
	v_exp_f32_e32 v147, v147
	v_exp_f32_e32 v148, v148
	v_exp_f32_e32 v149, v149
	v_exp_f32_e32 v150, v150
	v_exp_f32_e32 v151, v151
	v_add_f32_e32 v144, 1.0, v144
	v_add_f32_e32 v145, 1.0, v145
	v_add_f32_e32 v146, 1.0, v146
	v_add_f32_e32 v147, 1.0, v147
	v_add_f32_e32 v148, 1.0, v148
	v_rcp_f32_e32 v144, v144
	v_add_f32_e32 v149, 1.0, v149
	v_rcp_f32_e32 v145, v145
	v_add_f32_e32 v150, 1.0, v150
	v_rcp_f32_e32 v146, v146
	v_add_f32_e32 v151, 1.0, v151
	v_rcp_f32_e32 v147, v147
	v_rcp_f32_e32 v148, v148
	v_rcp_f32_e32 v149, v149
	v_rcp_f32_e32 v150, v150
	v_rcp_f32_e32 v151, v151
	v_mul_f32_e32 v144, 0xbf60028a, v144
	v_mul_f32_e32 v145, 0xbf60028a, v145
	v_pk_mul_f32 v[160:161], v[202:203], v[180:181] op_sel_hi:[1,0]
	v_mul_f32_e32 v146, 0xbf60028a, v146
	v_mul_f32_e32 v147, 0xbf60028a, v147
	v_pk_mul_f32 v[162:163], v[200:201], v[180:181] op_sel_hi:[1,0]
	v_exp_f32_e32 v144, v144
	v_exp_f32_e32 v145, v145
	v_xor_b32_e32 v157, 0x80000000, v161
	v_xor_b32_e32 v156, 0x80000000, v160
	v_exp_f32_e32 v146, v146
	v_exp_f32_e32 v147, v147
	v_xor_b32_e32 v158, 0x80000000, v162
	v_xor_b32_e32 v159, 0x80000000, v163
	v_pk_mul_f32 v[160:161], v[160:161], v[148:149]
	v_pk_mul_f32 v[162:163], v[162:163], v[150:151]
	v_pk_add_f32 v[150:151], v[150:151], -1.0 op_sel_hi:[1,0]
	v_pk_add_f32 v[148:149], v[148:149], -1.0 op_sel_hi:[1,0]
	v_pk_fma_f32 v[150:151], v[238:239], v[150:151], 1.0 op_sel_hi:[1,1,0]
	v_pk_fma_f32 v[148:149], v[236:237], v[148:149], 1.0 op_sel_hi:[1,1,0]
	v_pk_mul_f32 v[150:151], v[192:193], v[150:151]
	v_pk_mul_f32 v[148:149], v[194:195], v[148:149]
	ds_write_b128 v164, v[156:159] offset:64
	ds_write_b128 v164, v[144:147] offset:12352
	ds_write_b128 v164, v[160:163] offset:4160
	global_store_dwordx4 v[176:177], v[148:151], off offset:832
	ds_write_b128 v232, v[148:151] offset:512
	s_nop 0
	s_nop 0
	s_nop 0
	s_waitcnt vmcnt(7)
	v_add_f32_e32 v136, v136, v240
	s_waitcnt vmcnt(6)
	v_add_f32_e32 v140, v140, v208
	v_add_f32_e32 v142, v142, v210
	v_mul_f32_e32 v140, 0xbfb8aa3b, v140
	v_mul_f32_e32 v142, 0xbfb8aa3b, v142
	v_exp_f32_e32 v140, v140
	v_exp_f32_e32 v142, v142
	v_add_f32_e32 v137, v137, v241
	v_add_f32_e32 v138, v138, v242
	v_add_f32_e32 v140, 1.0, v140
	v_add_f32_e32 v142, 1.0, v142
	v_add_f32_e32 v139, v139, v243
	v_rcp_f32_e32 v152, v140
	v_mul_f32_e32 v136, 0xbfb8aa3b, v136
	v_add_f32_e32 v140, v141, v209
	v_mul_f32_e32 v137, 0xbfb8aa3b, v137
	v_rcp_f32_e32 v154, v142
	v_mul_f32_e32 v138, 0xbfb8aa3b, v138
	v_add_f32_e32 v142, v143, v211
	v_mul_f32_e32 v139, 0xbfb8aa3b, v139
	v_exp_f32_e32 v136, v136
	v_mul_f32_e32 v140, 0xbfb8aa3b, v140
	v_exp_f32_e32 v137, v137
	v_exp_f32_e32 v138, v138
	v_mul_f32_e32 v142, 0xbfb8aa3b, v142
	v_exp_f32_e32 v139, v139
	v_exp_f32_e32 v140, v140
	v_exp_f32_e32 v142, v142
	v_add_f32_e32 v136, 1.0, v136
	v_add_f32_e32 v137, 1.0, v137
	v_add_f32_e32 v138, 1.0, v138
	v_add_f32_e32 v139, 1.0, v139
	v_rcp_f32_e32 v136, v136
	v_add_f32_e32 v140, 1.0, v140
	v_rcp_f32_e32 v137, v137
	v_rcp_f32_e32 v138, v138
	v_add_f32_e32 v142, 1.0, v142
	v_rcp_f32_e32 v139, v139
	v_rcp_f32_e32 v153, v140
	v_rcp_f32_e32 v155, v142
	v_mul_f32_e32 v136, 0xbf60028a, v136
	v_mul_f32_e32 v137, 0xbf60028a, v137
	v_pk_mul_f32 v[148:149], v[198:199], v[180:181] op_sel_hi:[1,0]
	v_mul_f32_e32 v138, 0xbf60028a, v138
	v_mul_f32_e32 v139, 0xbf60028a, v139
	v_pk_mul_f32 v[150:151], v[196:197], v[180:181] op_sel_hi:[1,0]
	v_exp_f32_e32 v136, v136
	v_exp_f32_e32 v137, v137
	v_xor_b32_e32 v141, 0x80000000, v149
	v_xor_b32_e32 v140, 0x80000000, v148
	v_exp_f32_e32 v138, v138
	v_exp_f32_e32 v139, v139
	v_xor_b32_e32 v142, 0x80000000, v150
	v_xor_b32_e32 v143, 0x80000000, v151
	v_pk_mul_f32 v[148:149], v[148:149], v[152:153]
	v_pk_mul_f32 v[150:151], v[150:151], v[154:155]
	v_pk_add_f32 v[154:155], v[154:155], -1.0 op_sel_hi:[1,0]
	v_pk_add_f32 v[152:153], v[152:153], -1.0 op_sel_hi:[1,0]
	s_waitcnt vmcnt(5)
; #define GAS __attribute__((address_space(1)))
; #define LAS __attribute__((address_space(3)))
; __device__ __forceinline__ float sigmoidf_(float x) { return __builtin_amdgcn_rcpf(1.0f + __builtin_amdgcn_exp2f(-1.4426950408889634f * x)); }
; __device__ __forceinline__ float shx(float v, int o, int lane) { return __builtin_bit_cast(float, __builtin_amdgcn_ds_bpermute((lane ^ o) << 2, __builtin_bit_cast(int, v))); }
; #define LDS_WAIT() asm volatile("s_waitcnt lgkmcnt(0)" ::: "memory")
; template <int MODE>
; __device__ __forceinline__ void scan_prologue(const ScanP& P, int m0, int seqbase, int T, int h, int d, float* slab, LAS float* lw, float* bon, int lane) {
;     ...
;     for (int n = 0; n < 4; ++n) { const int c = 16 * n + 4 * fq, col = h * 64 + c;
;         const f32x4 w0 = *(const f32x4*)(P.w0 + col), a0 = *(const f32x4*)(P.a0 + col), ka = *(const f32x4*)(P.k_a + col);
;         f32x4 wv, bv, kd, av;
; #pragma unroll
;         for (int i = 0; i < 4; ++i) { const float ic = sigmoidf_(Da[n][i] + a0[i]);
;             wv[i] = __builtin_amdgcn_exp2f(-DECAY_SCALE * 1.4426950408889634f * sigmoidf_(Dw[n][i] + w0[i]));
;             const float kk = kk4[n][i] * rs; av[i] = -kk; bv[i] = kk * ic; kd[i] = k4[n][i] * (1.0f + (ic - 1.0f) * ka[i]); }
;         *(LAS f32x4*)(lw + fr * 64 + c) = av; *(LAS f32x4*)(lw + 3072 + fr * 64 + c) = wv; *(LAS f32x4*)(lw + (MODE == 3 ? 1024 : 4096) + fr * 64 + c) = bv;
;         if (MODE != 1) *(f32x4*)(srow + 192 + c) = kd;
;         { LAS float* xsel = (fr == (d ? 15 : 0)) ? lw + 2048 + c : lw + 2304 + lane * 4;
;           if (MODE != 1) *(LAS f32x4*)(xsel + 128) = kd; }
;         if (MODE == 2) { const f32x4 rk = *(const f32x4*)(P.r_k + col); const f32x4 t = r4[n] * kd * rk; bp += (t.x + t.y) + (t.z + t.w); }
;         if ((n & 1) == 1) asm volatile("" ::: "memory");
;     }
;     if (MODE == 2) { bp += shx(bp, 16, lane); bp += shx(bp, 32, lane); if (fq == 0) bon[(size_t)m * 8 + h] = 0.5f * bp; }
; template <int MODE>
; __device__ __forceinline__ void scan_item(const CAS Args* A, int l, int item, float* slab0, LAS float* ldsw, int lane) {
;     ...
;         const GAS float* sl = (const GAS float*)slab + lane;
;         LDS_WAIT();
;         float nw[1], nb[1], nk[1], nv[1];
;         { const LAS float* xl = ldsw + 2048 + lane; nw[0] = 0.f; nb[0] = 0.f; nk[0] = 0.f; nv[0] = 0.f; if (MODE != 1) { nk[0] = xl[128]; nv[0] = xl[192]; } }
	v_pk_fma_f32 v[146:147], v[206:207], v[154:155], 1.0 op_sel_hi:[1,1,0]
	v_pk_fma_f32 v[144:145], v[204:205], v[152:153], 1.0 op_sel_hi:[1,1,0]
	v_pk_mul_f32 v[146:147], v[188:189], v[146:147]
	v_pk_mul_f32 v[144:145], v[190:191], v[144:145]
	ds_write_b128 v164, v[140:143] offset:128
	ds_write_b128 v164, v[136:139] offset:12416
	ds_write_b128 v164, v[148:151] offset:4224
	global_store_dwordx4 v[176:177], v[144:147], off offset:896
	ds_write_b128 v230, v[144:147] offset:512
	s_nop 0
	s_nop 0
	s_nop 0
	s_waitcnt vmcnt(3)
	v_add_f32_e32 v132, v132, v248
	s_waitcnt vmcnt(2)
	v_add_f32_e32 v128, v128, v244
	v_add_f32_e32 v129, v129, v245
	v_add_f32_e32 v130, v130, v246
	v_add_f32_e32 v131, v131, v247
	v_mul_f32_e32 v128, 0xbfb8aa3b, v128
	v_add_f32_e32 v133, v133, v249
	v_mul_f32_e32 v129, 0xbfb8aa3b, v129
	v_add_f32_e32 v134, v134, v250
	v_mul_f32_e32 v130, 0xbfb8aa3b, v130
	v_add_f32_e32 v135, v135, v251
	v_mul_f32_e32 v131, 0xbfb8aa3b, v131
	v_mul_f32_e32 v132, 0xbfb8aa3b, v132
	v_exp_f32_e32 v128, v128
	v_mul_f32_e32 v133, 0xbfb8aa3b, v133
	v_exp_f32_e32 v129, v129
	v_mul_f32_e32 v134, 0xbfb8aa3b, v134
	v_exp_f32_e32 v130, v130
	v_mul_f32_e32 v135, 0xbfb8aa3b, v135
	v_exp_f32_e32 v131, v131
	v_exp_f32_e32 v132, v132
	v_exp_f32_e32 v133, v133
	v_exp_f32_e32 v134, v134
	v_exp_f32_e32 v135, v135
	v_add_f32_e32 v128, 1.0, v128
	v_add_f32_e32 v129, 1.0, v129
	v_add_f32_e32 v130, 1.0, v130
	v_add_f32_e32 v131, 1.0, v131
	v_add_f32_e32 v132, 1.0, v132
	v_rcp_f32_e32 v128, v128
	v_add_f32_e32 v133, 1.0, v133
	v_rcp_f32_e32 v129, v129
	v_add_f32_e32 v134, 1.0, v134
	v_rcp_f32_e32 v130, v130
	v_add_f32_e32 v135, 1.0, v135
	v_rcp_f32_e32 v131, v131
	v_rcp_f32_e32 v132, v132
	v_rcp_f32_e32 v133, v133
	v_rcp_f32_e32 v134, v134
	v_rcp_f32_e32 v135, v135
	v_mul_f32_e32 v128, 0xbf60028a, v128
	v_mul_f32_e32 v129, 0xbf60028a, v129
	v_pk_mul_f32 v[144:145], v[186:187], v[180:181] op_sel_hi:[1,0]
	v_mul_f32_e32 v130, 0xbf60028a, v130
	v_mul_f32_e32 v131, 0xbf60028a, v131
	v_pk_mul_f32 v[146:147], v[184:185], v[180:181] op_sel_hi:[1,0]
	v_exp_f32_e32 v128, v128
	v_exp_f32_e32 v129, v129
	v_xor_b32_e32 v141, 0x80000000, v145
	v_xor_b32_e32 v140, 0x80000000, v144
	v_exp_f32_e32 v130, v130
	v_exp_f32_e32 v131, v131
	v_xor_b32_e32 v142, 0x80000000, v146
	v_xor_b32_e32 v143, 0x80000000, v147
	v_pk_mul_f32 v[144:145], v[144:145], v[132:133]
	v_pk_mul_f32 v[146:147], v[146:147], v[134:135]
	v_pk_add_f32 v[134:135], v[134:135], -1.0 op_sel_hi:[1,0]
	v_pk_add_f32 v[132:133], v[132:133], -1.0 op_sel_hi:[1,0]
	v_pk_fma_f32 v[134:135], v[168:169], v[134:135], 1.0 op_sel_hi:[1,1,0]
	v_pk_fma_f32 v[132:133], v[166:167], v[132:133], 1.0 op_sel_hi:[1,1,0]
	v_pk_mul_f32 v[134:135], v[178:179], v[134:135]
	v_pk_mul_f32 v[132:133], v[182:183], v[132:133]
	ds_write_b128 v164, v[140:143] offset:192
	ds_write_b128 v164, v[128:131] offset:12480
	ds_write_b128 v164, v[144:147] offset:4288
	global_store_dwordx4 v[176:177], v[132:135], off offset:960
	ds_write_b128 v229, v[132:135] offset:512
	s_waitcnt lgkmcnt(0)
	ds_read2st64_b32 v[128:129], v228 offset0:34 offset1:35
	v_subrev_u32_e32 v244, s94, v228
	v_and_b32_e32 v245, 0xc0, v244
	v_and_b32_e32 v244, 60, v244
	v_add_u32_e32 v244, s94, v244
	v_sub_u32_e32 v240, 0, v245
	v_ashrrev_i32_e32 v241, 31, v240
	ds_read_b32 v232, v244 offset:8704
	ds_read_b32 v233, v244 offset:8768
	ds_read_b32 v234, v244 offset:8832
	ds_read_b32 v235, v244 offset:8896
	s_waitcnt lgkmcnt(0)
	v_mov_b32_e32 v130, v129
	s_setprio 1

; #define LAS __attribute__((address_space(3)))
; template <int MODE>
; __device__ __forceinline__ void scan_item(const CAS Args* A, int l, int item, float* slab0, LAS float* ldsw, int lane) {
;     ...
;             const LAS f32x4* ua = (const LAS f32x4*)(ldsw + s * 64); const LAS f32x4* ur = (const LAS f32x4*)(ldsw + 1024 + s * 64); const LAS f32x4* uw = (const LAS f32x4*)(ldsw + 3072 + s * 64); const LAS f32x4* ub = (const LAS f32x4*)(ldsw + (MODE == 3 ? 1024 : 4096) + s * 64);
;             f2 sa2 = (f2){0.f, 0.f}, sb2 = (f2){0.f, 0.f}, pa2 = (f2){0.f, 0.f}, pb2 = (f2){0.f, 0.f};
; #pragma unroll
;             for (int j = 0; j < 16; ++j) { const f32x4 aq = ua[j]; const f2 a0 = (f2){aq.x, aq.y}, a1 = (f2){aq.z, aq.w}; sa2 = S[2 * j] * a0 + sa2; sb2 = S[2 * j + 1] * a1 + sb2;
;                 if (MODE == 3) { pa2 = Pm[2 * j] * a0 + pa2; pb2 = Pm[2 * j + 1] * a1 + pb2; } }
;             const float sa = (sa2.x + sa2.y) + (sb2.x + sb2.y), pa = (pa2.x + pa2.y) + (pb2.x + pb2.y); const f2 pas = (f2){pa, pa};
.LBB0_292:
	s_lshl_b32 s5, s5, 8
	s_add_i32 s5, s94, s5
	v_mov_b32_e32 v170, s5
	ds_read_b128 v[136:139], v170
	ds_read_b128 v[144:147], v170 offset:16
	ds_read_b128 v[148:151], v170 offset:32
	ds_read_b128 v[152:155], v170 offset:48
	ds_read_b128 v[156:159], v170 offset:64
	ds_read_b128 v[160:163], v170 offset:80
	ds_read_b128 v[164:167], v170 offset:96
	ds_read_b128 v[176:179], v170 offset:112
	ds_read_b128 v[182:185], v170 offset:128
	ds_read_b128 v[186:189], v170 offset:144
	ds_read_b128 v[196:199], v170 offset:160
	ds_read_b128 v[200:203], v170 offset:176
	s_waitcnt lgkmcnt(11)
	v_pk_fma_f32 v[140:141], v[124:125], v[136:137], 0 op_sel_hi:[1,1,0]
	v_pk_fma_f32 v[142:143], v[126:127], v[138:139], 0 op_sel_hi:[1,1,0]
	v_pk_fma_f32 v[132:133], v[0:1], v[136:137], 0 op_sel_hi:[1,1,0]
	v_pk_fma_f32 v[134:135], v[2:3], v[138:139], 0 op_sel_hi:[1,1,0]
	s_waitcnt lgkmcnt(10)
	v_pk_fma_f32 v[140:141], v[120:121], v[144:145], v[140:141]
	v_pk_fma_f32 v[142:143], v[122:123], v[146:147], v[142:143]
	v_pk_fma_f32 v[132:133], v[4:5], v[144:145], v[132:133]
	v_pk_fma_f32 v[134:135], v[6:7], v[146:147], v[134:135]
	s_waitcnt lgkmcnt(9)
	v_pk_fma_f32 v[140:141], v[116:117], v[148:149], v[140:141]
	v_pk_fma_f32 v[142:143], v[118:119], v[150:151], v[142:143]
	v_pk_fma_f32 v[132:133], v[8:9], v[148:149], v[132:133]
	v_pk_fma_f32 v[134:135], v[10:11], v[150:151], v[134:135]
	s_waitcnt lgkmcnt(8)
	v_pk_fma_f32 v[140:141], v[112:113], v[152:153], v[140:141]
	v_pk_fma_f32 v[142:143], v[114:115], v[154:155], v[142:143]
	v_pk_fma_f32 v[132:133], v[12:13], v[152:153], v[132:133]
	v_pk_fma_f32 v[134:135], v[14:15], v[154:155], v[134:135]
	ds_read_b128 v[204:207], v170 offset:192
	ds_read_b128 v[208:211], v170 offset:208
	ds_read_b128 v[212:215], v170 offset:224
	ds_read_b128 v[246:249], v170 offset:240
	s_waitcnt lgkmcnt(11)
	v_pk_fma_f32 v[140:141], v[108:109], v[156:157], v[140:141]
	v_pk_fma_f32 v[142:143], v[110:111], v[158:159], v[142:143]
	v_pk_fma_f32 v[132:133], v[16:17], v[156:157], v[132:133]
	v_pk_fma_f32 v[134:135], v[18:19], v[158:159], v[134:135]
	s_waitcnt lgkmcnt(10)
	v_pk_fma_f32 v[140:141], v[104:105], v[160:161], v[140:141]
	v_pk_fma_f32 v[142:143], v[106:107], v[162:163], v[142:143]
	v_pk_fma_f32 v[132:133], v[20:21], v[160:161], v[132:133]
	v_pk_fma_f32 v[134:135], v[22:23], v[162:163], v[134:135]
	s_waitcnt lgkmcnt(9)
	v_pk_fma_f32 v[140:141], v[100:101], v[164:165], v[140:141]
	v_pk_fma_f32 v[142:143], v[102:103], v[166:167], v[142:143]
	v_pk_fma_f32 v[132:133], v[24:25], v[164:165], v[132:133]
	v_pk_fma_f32 v[134:135], v[26:27], v[166:167], v[134:135]
	s_waitcnt lgkmcnt(8)
	v_pk_fma_f32 v[140:141], v[96:97], v[176:177], v[140:141]
	v_pk_fma_f32 v[142:143], v[98:99], v[178:179], v[142:143]
	v_pk_fma_f32 v[132:133], v[28:29], v[176:177], v[132:133]
	v_pk_fma_f32 v[134:135], v[30:31], v[178:179], v[134:135]
	s_waitcnt lgkmcnt(7)
	v_pk_fma_f32 v[140:141], v[92:93], v[182:183], v[140:141]
	v_pk_fma_f32 v[142:143], v[94:95], v[184:185], v[142:143]
	v_pk_fma_f32 v[132:133], v[32:33], v[182:183], v[132:133]
	v_pk_fma_f32 v[134:135], v[34:35], v[184:185], v[134:135]
	s_waitcnt lgkmcnt(6)
	v_pk_fma_f32 v[140:141], v[88:89], v[186:187], v[140:141]
	v_pk_fma_f32 v[142:143], v[90:91], v[188:189], v[142:143]
	v_pk_fma_f32 v[132:133], v[36:37], v[186:187], v[132:133]
	v_pk_fma_f32 v[134:135], v[38:39], v[188:189], v[134:135]
	s_waitcnt lgkmcnt(5)
	v_pk_fma_f32 v[140:141], v[84:85], v[196:197], v[140:141]
	v_pk_fma_f32 v[142:143], v[86:87], v[198:199], v[142:143]
	v_pk_fma_f32 v[132:133], v[40:41], v[196:197], v[132:133]
	v_pk_fma_f32 v[134:135], v[42:43], v[198:199], v[134:135]
	s_waitcnt lgkmcnt(4)
	v_pk_fma_f32 v[140:141], v[80:81], v[200:201], v[140:141]
	v_pk_fma_f32 v[142:143], v[82:83], v[202:203], v[142:143]
	v_pk_fma_f32 v[132:133], v[44:45], v[200:201], v[132:133]
	v_pk_fma_f32 v[134:135], v[46:47], v[202:203], v[134:135]
	s_waitcnt lgkmcnt(3)
	v_pk_fma_f32 v[140:141], v[76:77], v[204:205], v[140:141]
	v_pk_fma_f32 v[142:143], v[78:79], v[206:207], v[142:143]
	v_pk_fma_f32 v[132:133], v[48:49], v[204:205], v[132:133]
	v_pk_fma_f32 v[134:135], v[50:51], v[206:207], v[134:135]
	s_waitcnt lgkmcnt(2)
	v_pk_fma_f32 v[140:141], v[72:73], v[208:209], v[140:141]
	v_pk_fma_f32 v[142:143], v[74:75], v[210:211], v[142:143]
	v_pk_fma_f32 v[132:133], v[52:53], v[208:209], v[132:133]
	v_pk_fma_f32 v[134:135], v[54:55], v[210:211], v[134:135]
	s_waitcnt lgkmcnt(1)
	v_pk_fma_f32 v[140:141], v[68:69], v[212:213], v[140:141]
	v_pk_fma_f32 v[142:143], v[70:71], v[214:215], v[142:143]
	v_pk_fma_f32 v[132:133], v[56:57], v[212:213], v[132:133]
	v_pk_fma_f32 v[134:135], v[58:59], v[214:215], v[134:135]
	s_waitcnt lgkmcnt(0)
	v_pk_fma_f32 v[140:141], v[64:65], v[246:247], v[140:141]
	v_pk_fma_f32 v[142:143], v[66:67], v[248:249], v[142:143]
	v_pk_fma_f32 v[132:133], v[60:61], v[246:247], v[132:133]
	v_pk_fma_f32 v[134:135], v[62:63], v[248:249], v[134:135]
	v_mov_b32_e32 v136, v142
	v_mov_b32_e32 v137, v140
	v_mov_b32_e32 v140, v143
	v_pk_add_f32 v[136:137], v[136:137], v[140:141]
	v_mov_b32_e32 v138, v134
	v_mov_b32_e32 v139, v132
	v_mov_b32_e32 v132, v135
	v_pk_add_f32 v[132:133], v[138:139], v[132:133]
	v_pk_add_f32 v[134:135], v[136:137], v[136:137] op_sel:[0,1] op_sel_hi:[0,1]
	ds_read_b128 v[136:139], v170 offset:12288
	ds_read_b128 v[140:143], v170 offset:12304
	ds_read_b128 v[144:147], v170 offset:4096
	ds_read_b128 v[148:151], v170 offset:4112
	ds_read_b128 v[152:155], v170 offset:12320
	ds_read_b128 v[156:159], v170 offset:12336
	ds_read_b128 v[160:163], v170 offset:4128
	ds_read_b128 v[164:167], v170 offset:4144
	v_pk_add_f32 v[132:133], v[132:133], v[132:133] op_sel:[0,1] op_sel_hi:[0,1]
	s_waitcnt lgkmcnt(5)
; #define RL2(x, j) (f2){__builtin_bit_cast(float, __builtin_amdgcn_readlane(__builtin_bit_cast(int, x), 2 * (j))), __builtin_bit_cast(float, __builtin_amdgcn_readlane(__builtin_bit_cast(int, x), 2 * (j) + 1))}
; template <int MODE>
; __device__ __forceinline__ void scan_item(const CAS Args* A, int l, int item, float* slab0, LAS float* ldsw, int lane) {
;     ...
;             f2 y2 = (f2){0.f, 0.f}, y3 = (f2){0.f, 0.f};
;             f32x4 nwq[2], nbq[2], nrq[2];
;             nwq[0] = uw[0]; nwq[1] = uw[1]; nbq[0] = ub[0]; nbq[1] = ub[1]; nrq[0] = (f32x4){0.f, 0.f, 0.f, 0.f}; nrq[1] = nrq[0];
;             if (MODE == 2) { nrq[0] = ur[0]; nrq[1] = ur[1]; }
; #pragma unroll
;             for (int g = 0; g < 8; ++g) {
;                 const f32x4 cwq0 = nwq[0], cwq1 = nwq[1], cbq0 = nbq[0], cbq1 = nbq[1], crq0 = nrq[0], crq1 = nrq[1];
;                 if (g < 7) { nwq[0] = uw[2 * g + 2]; nwq[1] = uw[2 * g + 3]; nbq[0] = ub[2 * g + 2]; nbq[1] = ub[2 * g + 3];
;                     if (MODE == 2) { nrq[0] = ur[2 * g + 2]; nrq[1] = ur[2 * g + 3]; } }
;                 f2 bb[4], ww[4], kq[4], rr[4];
;                 ww[0] = (f2){cwq0.x, cwq0.y}; ww[1] = (f2){cwq0.z, cwq0.w}; ww[2] = (f2){cwq1.x, cwq1.y}; ww[3] = (f2){cwq1.z, cwq1.w};
;                 bb[0] = (f2){cbq0.x, cbq0.y}; bb[1] = (f2){cbq0.z, cbq0.w}; bb[2] = (f2){cbq1.x, cbq1.y}; bb[3] = (f2){cbq1.z, cbq1.w};
;                 rr[0] = (f2){crq0.x, crq0.y}; rr[1] = (f2){crq0.z, crq0.w}; rr[2] = (f2){crq1.x, crq1.y}; rr[3] = (f2){crq1.z, crq1.w};
; #pragma unroll
;                 for (int q = 0; q < 4; ++q) { const int j = g * 4 + q; if (MODE != 1) kq[q] = RL2(ck, j); }
;                 __builtin_amdgcn_sched_barrier(0);
; #pragma unroll
;                 for (int q = 0; q < 4; ++q) { const int j = g * 4 + q;
;                     f2 t = sas * bb[q];
;                     if (MODE != 1) t = vvs * kq[q] + t;
;                     S[j] = S[j] * ww[q] + t;
;                     if (MODE == 3) Pm[j] = Pm[j] * ww[q] + pas * bb[q];
;                     if (MODE == 2) { if (j & 1) y3 = S[j] * rr[q] + y3; else y2 = S[j] * rr[q] + y2; } }
;             }
	v_pk_mul_f32 v[168:169], v[144:145], v[134:135]
	v_pk_mul_f32 v[144:145], v[144:145], v[132:133]
	v_pk_fma_f32 v[124:125], v[124:125], v[136:137], v[168:169]
	v_pk_fma_f32 v[0:1], v[0:1], v[136:137], v[144:145]
	v_pk_mul_f32 v[136:137], v[146:147], v[134:135]
	v_pk_fma_f32 v[126:127], v[126:127], v[138:139], v[136:137]
	v_fmac_f32_dpp v124, v232, v130 row_newbcast:0 row_mask:0xf bank_mask:0xf
	v_fmac_f32_dpp v125, v232, v130 row_newbcast:1 row_mask:0xf bank_mask:0xf
	v_pk_mul_f32 v[136:137], v[146:147], v[132:133]
	v_pk_fma_f32 v[2:3], v[2:3], v[138:139], v[136:137]
	s_waitcnt lgkmcnt(4)
	v_pk_mul_f32 v[136:137], v[148:149], v[134:135]
	v_pk_fma_f32 v[120:121], v[120:121], v[140:141], v[136:137]
	v_fmac_f32_dpp v126, v232, v130 row_newbcast:2 row_mask:0xf bank_mask:0xf
	v_fmac_f32_dpp v127, v232, v130 row_newbcast:3 row_mask:0xf bank_mask:0xf
	v_pk_mul_f32 v[136:137], v[148:149], v[132:133]
	v_pk_fma_f32 v[4:5], v[4:5], v[140:141], v[136:137]
	v_pk_mul_f32 v[136:137], v[150:151], v[134:135]
	v_pk_fma_f32 v[122:123], v[122:123], v[142:143], v[136:137]
	v_fmac_f32_dpp v120, v232, v130 row_newbcast:4 row_mask:0xf bank_mask:0xf
	v_fmac_f32_dpp v121, v232, v130 row_newbcast:5 row_mask:0xf bank_mask:0xf
	v_pk_mul_f32 v[136:137], v[150:151], v[132:133]
	v_pk_fma_f32 v[6:7], v[6:7], v[142:143], v[136:137]
	ds_read_b128 v[136:139], v170 offset:12352
	ds_read_b128 v[140:143], v170 offset:12368
	ds_read_b128 v[144:147], v170 offset:4160
	ds_read_b128 v[148:151], v170 offset:4176
	s_waitcnt lgkmcnt(5)
	v_pk_mul_f32 v[168:169], v[134:135], v[160:161]
	v_pk_mul_f32 v[160:161], v[132:133], v[160:161]
	v_pk_fma_f32 v[116:117], v[116:117], v[152:153], v[168:169]
	v_fmac_f32_dpp v122, v232, v130 row_newbcast:6 row_mask:0xf bank_mask:0xf
	v_fmac_f32_dpp v123, v232, v130 row_newbcast:7 row_mask:0xf bank_mask:0xf
	v_pk_fma_f32 v[8:9], v[8:9], v[152:153], v[160:161]
	v_pk_mul_f32 v[152:153], v[134:135], v[162:163]
	v_pk_fma_f32 v[118:119], v[118:119], v[154:155], v[152:153]
	v_fmac_f32_dpp v116, v232, v130 row_newbcast:8 row_mask:0xf bank_mask:0xf
	v_fmac_f32_dpp v117, v232, v130 row_newbcast:9 row_mask:0xf bank_mask:0xf
	v_pk_mul_f32 v[152:153], v[132:133], v[162:163]
	v_pk_fma_f32 v[10:11], v[10:11], v[154:155], v[152:153]
	s_waitcnt lgkmcnt(4)
	v_pk_mul_f32 v[152:153], v[134:135], v[164:165]
	v_pk_fma_f32 v[112:113], v[112:113], v[156:157], v[152:153]
	v_fmac_f32_dpp v118, v232, v130 row_newbcast:10 row_mask:0xf bank_mask:0xf
	v_fmac_f32_dpp v119, v232, v130 row_newbcast:11 row_mask:0xf bank_mask:0xf
	v_pk_mul_f32 v[152:153], v[132:133], v[164:165]
	v_pk_fma_f32 v[12:13], v[12:13], v[156:157], v[152:153]
	v_pk_mul_f32 v[152:153], v[134:135], v[166:167]
	v_pk_fma_f32 v[114:115], v[114:115], v[158:159], v[152:153]
	v_fmac_f32_dpp v112, v232, v130 row_newbcast:12 row_mask:0xf bank_mask:0xf
	v_fmac_f32_dpp v113, v232, v130 row_newbcast:13 row_mask:0xf bank_mask:0xf
	v_pk_mul_f32 v[152:153], v[132:133], v[166:167]
	v_pk_fma_f32 v[14:15], v[14:15], v[158:159], v[152:153]
	ds_read_b128 v[152:155], v170 offset:12384
	ds_read_b128 v[156:159], v170 offset:12400
	ds_read_b128 v[160:163], v170 offset:4192
	ds_read_b128 v[164:167], v170 offset:4208
	s_waitcnt lgkmcnt(5)
	v_pk_mul_f32 v[168:169], v[134:135], v[144:145]
	v_pk_mul_f32 v[144:145], v[132:133], v[144:145]
	v_pk_fma_f32 v[108:109], v[108:109], v[136:137], v[168:169]
	v_fmac_f32_dpp v114, v232, v130 row_newbcast:14 row_mask:0xf bank_mask:0xf
	v_fmac_f32_dpp v115, v232, v130 row_newbcast:15 row_mask:0xf bank_mask:0xf
	v_pk_fma_f32 v[16:17], v[16:17], v[136:137], v[144:145]
	v_pk_mul_f32 v[136:137], v[134:135], v[146:147]
	v_pk_fma_f32 v[110:111], v[110:111], v[138:139], v[136:137]
	v_fmac_f32_dpp v108, v233, v130 row_newbcast:0 row_mask:0xf bank_mask:0xf
	v_fmac_f32_dpp v109, v233, v130 row_newbcast:1 row_mask:0xf bank_mask:0xf
	v_pk_mul_f32 v[136:137], v[132:133], v[146:147]
	v_pk_fma_f32 v[18:19], v[18:19], v[138:139], v[136:137]
	s_waitcnt lgkmcnt(4)
	v_pk_mul_f32 v[136:137], v[134:135], v[148:149]
	v_pk_fma_f32 v[104:105], v[104:105], v[140:141], v[136:137]
	v_fmac_f32_dpp v110, v233, v130 row_newbcast:2 row_mask:0xf bank_mask:0xf
	v_fmac_f32_dpp v111, v233, v130 row_newbcast:3 row_mask:0xf bank_mask:0xf
	v_pk_mul_f32 v[136:137], v[132:133], v[148:149]
	v_pk_fma_f32 v[20:21], v[20:21], v[140:141], v[136:137]
	v_pk_mul_f32 v[136:137], v[134:135], v[150:151]
	v_pk_fma_f32 v[106:107], v[106:107], v[142:143], v[136:137]
	v_fmac_f32_dpp v104, v233, v130 row_newbcast:4 row_mask:0xf bank_mask:0xf
	v_fmac_f32_dpp v105, v233, v130 row_newbcast:5 row_mask:0xf bank_mask:0xf
	v_pk_mul_f32 v[136:137], v[132:133], v[150:151]
	v_pk_fma_f32 v[22:23], v[22:23], v[142:143], v[136:137]
	ds_read_b128 v[136:139], v170 offset:12416
	ds_read_b128 v[140:143], v170 offset:12432
	ds_read_b128 v[144:147], v170 offset:4224
	ds_read_b128 v[148:151], v170 offset:4240
	s_waitcnt lgkmcnt(5)
	v_pk_mul_f32 v[168:169], v[134:135], v[160:161]
	v_pk_mul_f32 v[160:161], v[132:133], v[160:161]
	v_pk_fma_f32 v[100:101], v[100:101], v[152:153], v[168:169]
	v_fmac_f32_dpp v106, v233, v130 row_newbcast:6 row_mask:0xf bank_mask:0xf
	v_fmac_f32_dpp v107, v233, v130 row_newbcast:7 row_mask:0xf bank_mask:0xf
	v_pk_fma_f32 v[24:25], v[24:25], v[152:153], v[160:161]
	v_pk_mul_f32 v[152:153], v[134:135], v[162:163]
	v_pk_fma_f32 v[102:103], v[102:103], v[154:155], v[152:153]
	v_fmac_f32_dpp v100, v233, v130 row_newbcast:8 row_mask:0xf bank_mask:0xf
	v_fmac_f32_dpp v101, v233, v130 row_newbcast:9 row_mask:0xf bank_mask:0xf
	v_pk_mul_f32 v[152:153], v[132:133], v[162:163]
	v_pk_fma_f32 v[26:27], v[26:27], v[154:155], v[152:153]
	s_waitcnt lgkmcnt(4)
; #define RL2(x, j) (f2){__builtin_bit_cast(float, __builtin_amdgcn_readlane(__builtin_bit_cast(int, x), 2 * (j))), __builtin_bit_cast(float, __builtin_amdgcn_readlane(__builtin_bit_cast(int, x), 2 * (j) + 1))}
; template <int MODE>
; __device__ __forceinline__ void scan_item(const CAS Args* A, int l, int item, float* slab0, LAS float* ldsw, int lane) {
;     ...
;             f2 y2 = (f2){0.f, 0.f}, y3 = (f2){0.f, 0.f};
;             f32x4 nwq[2], nbq[2], nrq[2];
;             nwq[0] = uw[0]; nwq[1] = uw[1]; nbq[0] = ub[0]; nbq[1] = ub[1]; nrq[0] = (f32x4){0.f, 0.f, 0.f, 0.f}; nrq[1] = nrq[0];
;             if (MODE == 2) { nrq[0] = ur[0]; nrq[1] = ur[1]; }
; #pragma unroll
;             for (int g = 0; g < 8; ++g) {
;                 const f32x4 cwq0 = nwq[0], cwq1 = nwq[1], cbq0 = nbq[0], cbq1 = nbq[1], crq0 = nrq[0], crq1 = nrq[1];
;                 if (g < 7) { nwq[0] = uw[2 * g + 2]; nwq[1] = uw[2 * g + 3]; nbq[0] = ub[2 * g + 2]; nbq[1] = ub[2 * g + 3];
;                     if (MODE == 2) { nrq[0] = ur[2 * g + 2]; nrq[1] = ur[2 * g + 3]; } }
;                 f2 bb[4], ww[4], kq[4], rr[4];
;                 ww[0] = (f2){cwq0.x, cwq0.y}; ww[1] = (f2){cwq0.z, cwq0.w}; ww[2] = (f2){cwq1.x, cwq1.y}; ww[3] = (f2){cwq1.z, cwq1.w};
;                 bb[0] = (f2){cbq0.x, cbq0.y}; bb[1] = (f2){cbq0.z, cbq0.w}; bb[2] = (f2){cbq1.x, cbq1.y}; bb[3] = (f2){cbq1.z, cbq1.w};
;                 rr[0] = (f2){crq0.x, crq0.y}; rr[1] = (f2){crq0.z, crq0.w}; rr[2] = (f2){crq1.x, crq1.y}; rr[3] = (f2){crq1.z, crq1.w};
; #pragma unroll
;                 for (int q = 0; q < 4; ++q) { const int j = g * 4 + q; if (MODE != 1) kq[q] = RL2(ck, j); }
;                 __builtin_amdgcn_sched_barrier(0);
; #pragma unroll
;                 for (int q = 0; q < 4; ++q) { const int j = g * 4 + q;
;                     f2 t = sas * bb[q];
;                     if (MODE != 1) t = vvs * kq[q] + t;
;                     S[j] = S[j] * ww[q] + t;
;                     if (MODE == 3) Pm[j] = Pm[j] * ww[q] + pas * bb[q];
;                     if (MODE == 2) { if (j & 1) y3 = S[j] * rr[q] + y3; else y2 = S[j] * rr[q] + y2; } }
;             }
	v_pk_mul_f32 v[152:153], v[134:135], v[164:165]
	v_pk_fma_f32 v[96:97], v[96:97], v[156:157], v[152:153]
	v_fmac_f32_dpp v102, v233, v130 row_newbcast:10 row_mask:0xf bank_mask:0xf
	v_fmac_f32_dpp v103, v233, v130 row_newbcast:11 row_mask:0xf bank_mask:0xf
	v_pk_mul_f32 v[152:153], v[132:133], v[164:165]
	v_pk_fma_f32 v[28:29], v[28:29], v[156:157], v[152:153]
	v_pk_mul_f32 v[152:153], v[134:135], v[166:167]
	v_pk_fma_f32 v[98:99], v[98:99], v[158:159], v[152:153]
	v_fmac_f32_dpp v96, v233, v130 row_newbcast:12 row_mask:0xf bank_mask:0xf
	v_fmac_f32_dpp v97, v233, v130 row_newbcast:13 row_mask:0xf bank_mask:0xf
	v_pk_mul_f32 v[152:153], v[132:133], v[166:167]
	v_pk_fma_f32 v[30:31], v[30:31], v[158:159], v[152:153]
	ds_read_b128 v[152:155], v170 offset:12448
	ds_read_b128 v[156:159], v170 offset:12464
	ds_read_b128 v[160:163], v170 offset:4256
	ds_read_b128 v[164:167], v170 offset:4272
	s_waitcnt lgkmcnt(5)
	v_pk_mul_f32 v[168:169], v[134:135], v[144:145]
	v_pk_mul_f32 v[144:145], v[132:133], v[144:145]
	v_pk_fma_f32 v[92:93], v[92:93], v[136:137], v[168:169]
	v_fmac_f32_dpp v98, v233, v130 row_newbcast:14 row_mask:0xf bank_mask:0xf
	v_fmac_f32_dpp v99, v233, v130 row_newbcast:15 row_mask:0xf bank_mask:0xf
	v_pk_fma_f32 v[32:33], v[32:33], v[136:137], v[144:145]
	v_pk_mul_f32 v[136:137], v[134:135], v[146:147]
	v_pk_fma_f32 v[94:95], v[94:95], v[138:139], v[136:137]
	v_fmac_f32_dpp v92, v234, v130 row_newbcast:0 row_mask:0xf bank_mask:0xf
	v_fmac_f32_dpp v93, v234, v130 row_newbcast:1 row_mask:0xf bank_mask:0xf
	v_pk_mul_f32 v[136:137], v[132:133], v[146:147]
	v_pk_fma_f32 v[34:35], v[34:35], v[138:139], v[136:137]
	s_waitcnt lgkmcnt(4)
	v_pk_mul_f32 v[136:137], v[134:135], v[148:149]
	v_pk_fma_f32 v[88:89], v[88:89], v[140:141], v[136:137]
	v_fmac_f32_dpp v94, v234, v130 row_newbcast:2 row_mask:0xf bank_mask:0xf
	v_fmac_f32_dpp v95, v234, v130 row_newbcast:3 row_mask:0xf bank_mask:0xf
	v_pk_mul_f32 v[136:137], v[132:133], v[148:149]
	v_pk_fma_f32 v[36:37], v[36:37], v[140:141], v[136:137]
	v_pk_mul_f32 v[136:137], v[134:135], v[150:151]
	v_pk_fma_f32 v[90:91], v[90:91], v[142:143], v[136:137]
	v_fmac_f32_dpp v88, v234, v130 row_newbcast:4 row_mask:0xf bank_mask:0xf
	v_fmac_f32_dpp v89, v234, v130 row_newbcast:5 row_mask:0xf bank_mask:0xf
	v_pk_mul_f32 v[136:137], v[132:133], v[150:151]
	v_pk_fma_f32 v[38:39], v[38:39], v[142:143], v[136:137]
	ds_read_b128 v[136:139], v170 offset:12480
	ds_read_b128 v[140:143], v170 offset:12496
	ds_read_b128 v[144:147], v170 offset:4288
	ds_read_b128 v[148:151], v170 offset:4304
	s_waitcnt lgkmcnt(5)
	v_pk_mul_f32 v[168:169], v[134:135], v[160:161]
	v_pk_mul_f32 v[160:161], v[132:133], v[160:161]
	v_pk_fma_f32 v[84:85], v[84:85], v[152:153], v[168:169]
	v_fmac_f32_dpp v90, v234, v130 row_newbcast:6 row_mask:0xf bank_mask:0xf
	v_fmac_f32_dpp v91, v234, v130 row_newbcast:7 row_mask:0xf bank_mask:0xf
	v_pk_fma_f32 v[40:41], v[40:41], v[152:153], v[160:161]
	v_pk_mul_f32 v[152:153], v[134:135], v[162:163]
	v_pk_fma_f32 v[86:87], v[86:87], v[154:155], v[152:153]
	v_fmac_f32_dpp v84, v234, v130 row_newbcast:8 row_mask:0xf bank_mask:0xf
	v_fmac_f32_dpp v85, v234, v130 row_newbcast:9 row_mask:0xf bank_mask:0xf
	v_pk_mul_f32 v[152:153], v[132:133], v[162:163]
	v_pk_fma_f32 v[42:43], v[42:43], v[154:155], v[152:153]
	s_waitcnt lgkmcnt(4)
	v_pk_mul_f32 v[152:153], v[134:135], v[164:165]
	v_pk_fma_f32 v[80:81], v[80:81], v[156:157], v[152:153]
	v_fmac_f32_dpp v86, v234, v130 row_newbcast:10 row_mask:0xf bank_mask:0xf
	v_fmac_f32_dpp v87, v234, v130 row_newbcast:11 row_mask:0xf bank_mask:0xf
	v_pk_mul_f32 v[152:153], v[132:133], v[164:165]
	v_pk_fma_f32 v[44:45], v[44:45], v[156:157], v[152:153]
	v_pk_mul_f32 v[152:153], v[134:135], v[166:167]
	v_pk_fma_f32 v[82:83], v[82:83], v[158:159], v[152:153]
	v_fmac_f32_dpp v80, v234, v130 row_newbcast:12 row_mask:0xf bank_mask:0xf
	v_fmac_f32_dpp v81, v234, v130 row_newbcast:13 row_mask:0xf bank_mask:0xf
	v_pk_mul_f32 v[152:153], v[132:133], v[166:167]
	v_pk_fma_f32 v[46:47], v[46:47], v[158:159], v[152:153]
	ds_read_b128 v[152:155], v170 offset:12512
	ds_read_b128 v[156:159], v170 offset:12528
	ds_read_b128 v[160:163], v170 offset:4320
	ds_read_b128 v[164:167], v170 offset:4336
	s_waitcnt lgkmcnt(5)
; #define GAS __attribute__((address_space(1)))
; #define RL2(x, j) (f2){__builtin_bit_cast(float, __builtin_amdgcn_readlane(__builtin_bit_cast(int, x), 2 * (j))), __builtin_bit_cast(float, __builtin_amdgcn_readlane(__builtin_bit_cast(int, x), 2 * (j) + 1))}
; template <int MODE>
; __device__ __forceinline__ void scan_item(const CAS Args* A, int l, int item, float* slab0, LAS float* ldsw, int lane) {
;     ...
;         for (int st = 0; st < 16; ++st) {
;             const int s = d ? 15 - st : st;
;             const float cw = nw[0], cb = nb[0], ck = nk[0], vv = nv[0];
;             if (st < 15) { const GAS float* p = sl + (d ? s - 1 : s + 1) * 384;  if (MODE != 1) { nk[0] = p[192]; nv[0] = p[320]; } }
;     ...
;             for (int g = 0; g < 8; ++g) {
;                 const f32x4 cwq0 = nwq[0], cwq1 = nwq[1], cbq0 = nbq[0], cbq1 = nbq[1], crq0 = nrq[0], crq1 = nrq[1];
;                 if (g < 7) { nwq[0] = uw[2 * g + 2]; nwq[1] = uw[2 * g + 3]; nbq[0] = ub[2 * g + 2]; nbq[1] = ub[2 * g + 3];
;                     if (MODE == 2) { nrq[0] = ur[2 * g + 2]; nrq[1] = ur[2 * g + 3]; } }
;                 f2 bb[4], ww[4], kq[4], rr[4];
;                 ww[0] = (f2){cwq0.x, cwq0.y}; ww[1] = (f2){cwq0.z, cwq0.w}; ww[2] = (f2){cwq1.x, cwq1.y}; ww[3] = (f2){cwq1.z, cwq1.w};
;                 bb[0] = (f2){cbq0.x, cbq0.y}; bb[1] = (f2){cbq0.z, cbq0.w}; bb[2] = (f2){cbq1.x, cbq1.y}; bb[3] = (f2){cbq1.z, cbq1.w};
;                 rr[0] = (f2){crq0.x, crq0.y}; rr[1] = (f2){crq0.z, crq0.w}; rr[2] = (f2){crq1.x, crq1.y}; rr[3] = (f2){crq1.z, crq1.w};
; #pragma unroll
;                 for (int q = 0; q < 4; ++q) { const int j = g * 4 + q; if (MODE != 1) kq[q] = RL2(ck, j); }
;                 __builtin_amdgcn_sched_barrier(0);
; #pragma unroll
;                 for (int q = 0; q < 4; ++q) { const int j = g * 4 + q;
;                     f2 t = sas * bb[q];
;                     if (MODE != 1) t = vvs * kq[q] + t;
;                     S[j] = S[j] * ww[q] + t;
;                     if (MODE == 3) Pm[j] = Pm[j] * ww[q] + pas * bb[q];
;                     if (MODE == 2) { if (j & 1) y3 = S[j] * rr[q] + y3; else y2 = S[j] * rr[q] + y2; } }
;             }
	v_pk_mul_f32 v[168:169], v[134:135], v[144:145]
	v_pk_mul_f32 v[144:145], v[132:133], v[144:145]
	v_pk_fma_f32 v[76:77], v[76:77], v[136:137], v[168:169]
	v_fmac_f32_dpp v82, v234, v130 row_newbcast:14 row_mask:0xf bank_mask:0xf
	v_fmac_f32_dpp v83, v234, v130 row_newbcast:15 row_mask:0xf bank_mask:0xf
	v_pk_fma_f32 v[48:49], v[48:49], v[136:137], v[144:145]
	v_pk_mul_f32 v[136:137], v[134:135], v[146:147]
	v_pk_fma_f32 v[78:79], v[78:79], v[138:139], v[136:137]
	v_fmac_f32_dpp v76, v235, v130 row_newbcast:0 row_mask:0xf bank_mask:0xf
	v_fmac_f32_dpp v77, v235, v130 row_newbcast:1 row_mask:0xf bank_mask:0xf
	v_pk_mul_f32 v[136:137], v[132:133], v[146:147]
	v_pk_fma_f32 v[50:51], v[50:51], v[138:139], v[136:137]
	s_waitcnt lgkmcnt(4)
	v_pk_mul_f32 v[136:137], v[134:135], v[148:149]
	v_pk_fma_f32 v[72:73], v[72:73], v[140:141], v[136:137]
	v_fmac_f32_dpp v78, v235, v130 row_newbcast:2 row_mask:0xf bank_mask:0xf
	v_fmac_f32_dpp v79, v235, v130 row_newbcast:3 row_mask:0xf bank_mask:0xf
	v_pk_mul_f32 v[136:137], v[132:133], v[148:149]
	v_pk_fma_f32 v[52:53], v[52:53], v[140:141], v[136:137]
	v_pk_mul_f32 v[136:137], v[134:135], v[150:151]
	v_pk_fma_f32 v[74:75], v[74:75], v[142:143], v[136:137]
	v_fmac_f32_dpp v72, v235, v130 row_newbcast:4 row_mask:0xf bank_mask:0xf
	v_fmac_f32_dpp v73, v235, v130 row_newbcast:5 row_mask:0xf bank_mask:0xf
	v_pk_mul_f32 v[136:137], v[132:133], v[150:151]
	v_pk_fma_f32 v[54:55], v[54:55], v[142:143], v[136:137]
	s_waitcnt lgkmcnt(1)
	v_pk_mul_f32 v[136:137], v[134:135], v[160:161]
	s_add_i32 s4, s4, 1
	v_pk_fma_f32 v[68:69], v[68:69], v[152:153], v[136:137]
	v_fmac_f32_dpp v74, v235, v130 row_newbcast:6 row_mask:0xf bank_mask:0xf
	v_fmac_f32_dpp v75, v235, v130 row_newbcast:7 row_mask:0xf bank_mask:0xf
	v_pk_mul_f32 v[136:137], v[132:133], v[160:161]
	s_add_i32 s91, s91, -1
	v_pk_fma_f32 v[56:57], v[56:57], v[152:153], v[136:137]
	v_pk_mul_f32 v[136:137], v[134:135], v[162:163]
	s_cmp_eq_u32 s4, 16
	v_pk_fma_f32 v[70:71], v[70:71], v[154:155], v[136:137]
	v_fmac_f32_dpp v68, v235, v130 row_newbcast:8 row_mask:0xf bank_mask:0xf
	v_fmac_f32_dpp v69, v235, v130 row_newbcast:9 row_mask:0xf bank_mask:0xf
	v_pk_mul_f32 v[136:137], v[132:133], v[162:163]
	s_nop 0
	v_pk_fma_f32 v[58:59], v[58:59], v[154:155], v[136:137]
	s_waitcnt lgkmcnt(0)
	v_pk_mul_f32 v[136:137], v[134:135], v[164:165]
	s_nop 0
	v_pk_fma_f32 v[64:65], v[64:65], v[156:157], v[136:137]
	v_fmac_f32_dpp v70, v235, v130 row_newbcast:10 row_mask:0xf bank_mask:0xf
	v_fmac_f32_dpp v71, v235, v130 row_newbcast:11 row_mask:0xf bank_mask:0xf
	v_pk_mul_f32 v[136:137], v[132:133], v[164:165]
	v_pk_mul_f32 v[132:133], v[132:133], v[166:167]
	v_pk_fma_f32 v[60:61], v[60:61], v[156:157], v[136:137]
	v_pk_mul_f32 v[134:135], v[134:135], v[166:167]
	v_pk_fma_f32 v[62:63], v[62:63], v[158:159], v[132:133]
	v_pk_fma_f32 v[66:67], v[66:67], v[158:159], v[134:135]
	v_fmac_f32_dpp v64, v235, v130 row_newbcast:12 row_mask:0xf bank_mask:0xf
	v_fmac_f32_dpp v65, v235, v130 row_newbcast:13 row_mask:0xf bank_mask:0xf
	v_fmac_f32_dpp v66, v235, v130 row_newbcast:14 row_mask:0xf bank_mask:0xf
	v_fmac_f32_dpp v67, v235, v130 row_newbcast:15 row_mask:0xf bank_mask:0xf
	s_cbranch_scc1 .LBB0_288
	s_waitcnt vmcnt(0)
	v_mov_b32_e32 v232, v236
	v_mov_b32_e32 v233, v237
	v_mov_b32_e32 v234, v238
	v_mov_b32_e32 v235, v239
	v_mov_b32_e32 v130, v129
	s_branch .LBB0_290

; #define lane LANE_()
; template <int MODE>
; __device__ __forceinline__ void scan_prologue(const ScanP& P, int m0, int seqbase, int T, int h, int d, float* slab, LAS float* lw, float* bon, int lane) {
;     const int fr = lane & 15, fq = lane >> 4, m = m0 + fr, pos = m - seqbase; const bool hp = pos > 0, hn = pos < T - 1;
;     float* srow = slab + fr * 384;
;     f32x4 k4[4], kk4[4], r4[4]; float ss = 0.f;
;     v2u pk_[4][3], pv_[4][3], pr_[4][3];
;     const int offp_ = hp ? -PRP : 0, offn_ = hn ? PRP : 0; const unsigned mp_ = hp ? 0xffffffffu : 0u, mn_ = hn ? 0xffffffffu : 0u;
; #pragma unroll
;     for (int n = 0; n < 4; ++n) { const bf16* p = P.proj + (size_t)m * PRP + h * 64 + 16 * n + 4 * fq;
;         { v2u t; pk_[n][1] = *(const v2u*)(p + 512);
;           t = *(const v2u*)(p + 512 + offp_); pk_[n][0] = (v2u){t.x & mp_, t.y & mp_};
;           t = *(const v2u*)(p + 512 + offn_); pk_[n][2] = (v2u){t.x & mn_, t.y & mn_};
;           if (MODE != 1) { pv_[n][1] = *(const v2u*)(p + 1024);
;             t = *(const v2u*)(p + 1024 + offp_); pv_[n][0] = (v2u){t.x & mp_, t.y & mp_};
;             t = *(const v2u*)(p + 1024 + offn_); pv_[n][2] = (v2u){t.x & mn_, t.y & mn_}; }
;           if (MODE == 2) { pr_[n][1] = *(const v2u*)(p);
;             t = *(const v2u*)(p + offp_); pr_[n][0] = (v2u){t.x & mp_, t.y & mp_};
;             t = *(const v2u*)(p + offn_); pr_[n][2] = (v2u){t.x & mn_, t.y & mn_}; } } }
;     v4u xw_[2]; bf16x8 xa_[2];
; #pragma unroll
;     for (int ks = 0; ks < 2; ++ks) { xw_[ks] = *(const v4u*)(P.proj + (size_t)m * PRP + 1536 + d * 64 + ks * 32 + 8 * fq); xa_[ks] = *(const bf16x8*)(P.proj + (size_t)m * PRP + 1664 + d * 64 + ks * 32 + 8 * fq); }
.LBB0_549:
	s_not_b32 s4, s11
	s_add_i32 s8, s3, s4
	s_and_b64 s[4:5], s[82:83], exec
	s_cselect_b32 s4, s11, s8
	s_lshl_b32 s44, s4, 4
	v_mov_b32_e32 v184, v128
	s_add_i32 s44, s44, s47
	s_lshl_b32 s14, s53, 1
	v_and_b32_e32 v178, 15, v184
	v_or_b32_e32 v138, s44, v178
	v_subrev_u32_e32 v64, s52, v138
	v_ashrrev_i32_e32 v139, 31, v138
	v_ashrrev_i32_e32 v90, 4, v184
	v_cmp_lt_i32_e64 s[4:5], 0, v64
	v_cmp_gt_i32_e32 vcc, s46, v64
	s_waitcnt vmcnt(1)
	v_lshlrev_b64 v[64:65], 12, v[138:139]
	v_lshl_add_u64 v[80:81], s[60:61], 0, v[64:65]
	v_lshlrev_b32_e32 v64, 2, v90
	v_lshl_add_u64 v[68:69], v[80:81], 0, s[14:15]
	v_ashrrev_i32_e32 v65, 31, v64
	v_cndmask_b32_e64 v67, 0, -1, s[4:5]
	v_cndmask_b32_e64 v66, 0, v224, s[4:5]
	v_lshl_add_u64 v[86:87], v[64:65], 1, v[68:69]
	v_lshl_add_u64 v[84:85], v[86:87], 0, v[66:67]
	global_load_dwordx2 v[70:71], v[86:87], off offset:1024
	global_load_dwordx2 v[208:209], v[86:87], off offset:2048
	global_load_dwordx2 v[72:73], v[84:85], off offset:2048
	global_load_dwordx2 v[210:211], v[86:87], off
	global_load_dwordx2 v[76:77], v[84:85], off
	global_load_dwordx2 v[212:213], v[86:87], off offset:1056
	global_load_dwordx2 v[88:89], v[84:85], off offset:1056
	global_load_dwordx2 v[214:215], v[86:87], off offset:2080
	global_load_dwordx2 v[94:95], v[84:85], off offset:2080
	global_load_dwordx2 v[216:217], v[86:87], off offset:32
	global_load_dwordx2 v[100:101], v[84:85], off offset:32
	global_load_dwordx2 v[228:229], v[86:87], off offset:1088
	global_load_dwordx2 v[104:105], v[84:85], off offset:1088
	global_load_dwordx2 v[126:127], v[86:87], off offset:2112
	global_load_dwordx2 v[118:119], v[84:85], off offset:2112
	global_load_dwordx2 v[230:231], v[86:87], off offset:64
	global_load_dwordx2 v[124:125], v[84:85], off offset:64
	global_load_dwordx2 v[232:233], v[86:87], off offset:1120
	global_load_dwordx2 v[154:155], v[84:85], off offset:1120
	global_load_dwordx2 v[234:235], v[86:87], off offset:2144
	global_load_dwordx2 v[164:165], v[84:85], off offset:2144
	global_load_dwordx2 v[236:237], v[86:87], off offset:96
	global_load_dwordx2 v[200:201], v[84:85], off offset:96
	global_load_dwordx2 v[66:67], v[84:85], off offset:1024
	v_cndmask_b32_e32 v180, 0, v219, vcc
	v_lshl_add_u64 v[82:83], v[86:87], 0, v[180:181]
	global_load_dwordx2 v[68:69], v[82:83], off offset:1024
	global_load_dwordx2 v[74:75], v[82:83], off offset:2048
	global_load_dwordx2 v[78:79], v[82:83], off
	global_load_dwordx2 v[92:93], v[82:83], off offset:1056
	global_load_dwordx2 v[98:99], v[82:83], off offset:2080
	global_load_dwordx2 v[102:103], v[82:83], off offset:32
	global_load_dwordx2 v[106:107], v[82:83], off offset:1088
	global_load_dwordx2 v[120:121], v[82:83], off offset:2112
	global_load_dwordx2 v[152:153], v[82:83], off offset:64
	global_load_dwordx2 v[162:163], v[82:83], off offset:1120
	global_load_dwordx2 v[182:183], v[82:83], off offset:2144
	global_load_dwordx2 v[202:203], v[82:83], off offset:96
	s_nop 0
	v_mul_u32_u24_e32 v96, 0x180, v178
	v_lshlrev_b32_e32 v180, 2, v96
	v_lshl_add_u32 v108, v184, 4, s94
	v_lshl_add_u64 v[96:97], s[56:57], 0, v[180:181]
	v_add_u32_e32 v180, 0x2400, v108
	v_add_u32_e32 v108, s53, v64
	v_ashrrev_i32_e32 v109, 31, v108
	v_lshlrev_b64 v[150:151], 2, v[108:109]
	v_lshl_add_u64 v[110:111], s[62:63], 0, v[150:151]
	global_load_dwordx4 v[204:207], v[110:111], off offset:2048
	s_mov_b32 s85, s15
	v_lshlrev_b32_e32 v170, 3, v90
	v_lshl_add_u64 v[80:81], v[80:81], 0, s[84:85]
	v_ashrrev_i32_e32 v171, 31, v170
	v_lshl_add_u64 v[80:81], v[170:171], 1, v[80:81]
	global_load_dwordx4 v[238:241], v[80:81], off offset:3072
	global_load_dwordx4 v[242:245], v[80:81], off offset:3328
	global_load_dwordx4 v[246:249], v[80:81], off offset:3136
	v_lshlrev_b32_e32 v185, 8, v178
	s_waitcnt vmcnt(16)
	v_cndmask_b32_e64 v167, 0, v66, s[4:5]
	v_cndmask_b32_e64 v175, 0, v67, s[4:5]
	s_nop 0
	v_lshlrev_b32_e32 v186, 16, v70
	v_and_b32_e32 v187, 0xffff0000, v70
	v_lshlrev_b32_e32 v70, 16, v71
	v_and_b32_e32 v71, 0xffff0000, v71
	v_lshlrev_b32_e32 v166, 16, v167
	v_and_b32_e32 v167, 0xffff0000, v167
	v_lshlrev_b32_e32 v174, 16, v175
	v_and_b32_e32 v175, 0xffff0000, v175
	s_waitcnt vmcnt(15)
	v_cndmask_b32_e32 v188, 0, v68, vcc
	v_cndmask_b32_e32 v193, 0, v69, vcc
	s_nop 0
	s_nop 0
	v_cndmask_b32_e64 v141, 0, v72, s[4:5]
	v_cndmask_b32_e64 v140, 0, v73, s[4:5]
	s_nop 0
	s_waitcnt vmcnt(14)
	v_cndmask_b32_e32 v117, 0, v74, vcc
	v_cndmask_b32_e32 v116, 0, v75, vcc
	s_nop 0
	s_nop 0
	v_cndmask_b32_e64 v115, 0, v76, s[4:5]
	v_cndmask_b32_e64 v114, 0, v77, s[4:5]
	s_nop 0
	s_waitcnt vmcnt(13)
	v_cndmask_b32_e32 v113, 0, v78, vcc
	v_cndmask_b32_e32 v112, 0, v79, vcc
	global_load_dwordx4 v[76:79], v[110:111], off
	s_nop 0
	s_nop 0
	v_cndmask_b32_e64 v145, 0, v88, s[4:5]
	v_cndmask_b32_e64 v144, 0, v89, s[4:5]
	global_load_dwordx4 v[88:91], v[110:111], off offset:2112
	s_nop 0
	s_waitcnt vmcnt(14)
	v_cndmask_b32_e32 v143, 0, v92, vcc
	v_cndmask_b32_e32 v142, 0, v93, vcc
	s_nop 0
	s_nop 0
	v_cndmask_b32_e64 v157, 0, v94, s[4:5]
	v_cndmask_b32_e64 v156, 0, v95, s[4:5]
	s_nop 0
	s_waitcnt vmcnt(13)
	v_cndmask_b32_e32 v147, 0, v98, vcc
	v_cndmask_b32_e32 v146, 0, v99, vcc
	s_nop 0
	s_nop 0
	v_cndmask_b32_e64 v123, 0, v100, s[4:5]
	v_cndmask_b32_e64 v122, 0, v101, s[4:5]
	s_nop 0
	s_waitcnt vmcnt(12)
	v_cndmask_b32_e32 v99, 0, v102, vcc
	v_cndmask_b32_e32 v98, 0, v103, vcc
	s_nop 0
	s_nop 0
	v_cndmask_b32_e64 v160, 0, v104, s[4:5]
	v_cndmask_b32_e64 v158, 0, v105, s[4:5]
	s_nop 0
	s_waitcnt vmcnt(11)
	v_cndmask_b32_e32 v149, 0, v106, vcc
	v_cndmask_b32_e32 v148, 0, v107, vcc
	s_nop 0
	s_nop 0
	v_cndmask_b32_e64 v159, 0, v118, s[4:5]
	v_cndmask_b32_e64 v161, 0, v119, s[4:5]
	s_nop 0
	s_waitcnt vmcnt(10)
; #define LAS __attribute__((address_space(3)))
; #define lane LANE_()
; template <int MODE>
; __device__ __forceinline__ void scan_prologue(const ScanP& P, int m0, int seqbase, int T, int h, int d, float* slab, LAS float* lw, float* bon, int lane) {
;     ...
;     const int offp_ = hp ? -PRP : 0, offn_ = hn ? PRP : 0; const unsigned mp_ = hp ? 0xffffffffu : 0u, mn_ = hn ? 0xffffffffu : 0u;
; #pragma unroll
;     for (int n = 0; n < 4; ++n) { const bf16* p = P.proj + (size_t)m * PRP + h * 64 + 16 * n + 4 * fq;
;         { v2u t; pk_[n][1] = *(const v2u*)(p + 512);
;           t = *(const v2u*)(p + 512 + offp_); pk_[n][0] = (v2u){t.x & mp_, t.y & mp_};
;           t = *(const v2u*)(p + 512 + offn_); pk_[n][2] = (v2u){t.x & mn_, t.y & mn_};
;           if (MODE != 1) { pv_[n][1] = *(const v2u*)(p + 1024);
;             t = *(const v2u*)(p + 1024 + offp_); pv_[n][0] = (v2u){t.x & mp_, t.y & mp_};
;             t = *(const v2u*)(p + 1024 + offn_); pv_[n][2] = (v2u){t.x & mn_, t.y & mn_}; }
;           if (MODE == 2) { pr_[n][1] = *(const v2u*)(p);
;             t = *(const v2u*)(p + offp_); pr_[n][0] = (v2u){t.x & mp_, t.y & mp_};
;             t = *(const v2u*)(p + offn_); pr_[n][2] = (v2u){t.x & mn_, t.y & mn_}; } } }
;     v4u xw_[2]; bf16x8 xa_[2];
; #pragma unroll
;     for (int ks = 0; ks < 2; ++ks) { xw_[ks] = *(const v4u*)(P.proj + (size_t)m * PRP + 1536 + d * 64 + ks * 32 + 8 * fq); xa_[ks] = *(const bf16x8*)(P.proj + (size_t)m * PRP + 1664 + d * 64 + ks * 32 + 8 * fq); }
;     asm volatile("" ::: "memory");
;     ...
; #pragma unroll
;     for (int n = 0; n < 4; ++n) { const int c = 16 * n + 4 * fq, col = h * 64 + c;
;         k4[n] = CONV3_(pk_, 1);
;         if (MODE != 1) { const f32x4 v4 = CONV3_(pv_, 2); *(f32x4*)(srow + 320 + c) = v4; LAS float* xsel = (fr == (d ? 15 : 0)) ? lw + 2048 + c : lw + 2304 + lane * 4; *(LAS f32x4*)(xsel + 192) = v4; }
	v_cndmask_b32_e32 v198, 0, v120, vcc
	v_cndmask_b32_e32 v189, 0, v121, vcc
	s_nop 0
	s_nop 0
	v_cndmask_b32_e64 v173, 0, v124, s[4:5]
	v_cndmask_b32_e64 v172, 0, v125, s[4:5]
	s_nop 0
	s_waitcnt vmcnt(9)
	v_cndmask_b32_e32 v169, 0, v152, vcc
	v_cndmask_b32_e32 v168, 0, v153, vcc
	s_nop 0
	s_nop 0
	v_cndmask_b32_e64 v195, 0, v154, s[4:5]
	v_cndmask_b32_e64 v194, 0, v155, s[4:5]
	s_nop 0
	s_waitcnt vmcnt(8)
	v_cndmask_b32_e32 v197, 0, v162, vcc
	v_cndmask_b32_e32 v196, 0, v163, vcc
	s_nop 0
	s_nop 0
	v_cndmask_b32_e64 v192, 0, v164, s[4:5]
	v_cndmask_b32_e64 v191, 0, v165, s[4:5]
	s_nop 0
	s_nop 0
	s_nop 0
	s_nop 0
	s_waitcnt vmcnt(7)
	v_cndmask_b32_e32 v182, 0, v182, vcc
	s_nop 0
	v_cndmask_b32_e64 v177, 0, v200, s[4:5]
	v_cndmask_b32_e64 v176, 0, v201, s[4:5]
	v_add_co_u32_e64 v124, s[4:5], s45, v110
	v_cndmask_b32_e32 v179, 0, v183, vcc
	s_nop 0
	v_addc_co_u32_e64 v125, s[4:5], 0, v111, s[4:5]
	global_load_dwordx4 v[92:95], v[124:125], off offset:64
	v_add_co_u32_e64 v108, s[4:5], s96, v110
	s_waitcnt vmcnt(7)
	v_cndmask_b32_e32 v190, 0, v202, vcc
	v_cndmask_b32_e32 v183, 0, v203, vcc
	s_nop 0
	s_nop 0
	s_nop 0
	s_nop 0
	global_load_dwordx4 v[80:83], v[80:81], off offset:3392
	v_addc_co_u32_e64 v109, s[4:5], 0, v111, s[4:5]
	global_load_dwordx4 v[152:155], v[108:109], off offset:-4096
	global_load_dwordx4 v[162:165], v[108:109], off offset:2048
	global_load_dwordx4 v[84:87], v[108:109], off
	global_load_dwordx4 v[100:103], v[108:109], off offset:2112
	s_nop 0
	s_nop 0
	s_nop 0
	v_cmp_eq_u32_e32 vcc, s48, v178
	s_waitcnt vmcnt(3)
	v_pk_mul_f32 v[70:71], v[154:155], v[70:71]
	v_pk_mul_f32 v[152:153], v[152:153], v[186:187]
	v_pk_fma_f32 v[70:71], v[206:207], v[174:175], v[70:71]
	v_pk_fma_f32 v[118:119], v[204:205], v[166:167], v[152:153]
	v_lshlrev_b32_e32 v120, 16, v188
	v_and_b32_e32 v121, 0xffff0000, v188
	v_lshl_add_u64 v[174:175], s[70:71], 0, v[150:151]
	global_load_dwordx4 v[72:75], v[174:175], off
	global_load_dwordx4 v[104:107], v[174:175], off offset:64
	s_waitcnt vmcnt(4)
	v_pk_fma_f32 v[154:155], v[162:163], v[120:121], v[118:119]
	v_add_co_u32_e64 v120, s[4:5], s26, v174
	v_lshlrev_b32_e32 v152, 16, v193
	s_nop 0
	v_addc_co_u32_e64 v121, s[4:5], 0, v175, s[4:5]
	global_load_dwordx4 v[200:203], v[120:121], off offset:2048
	v_and_b32_e32 v153, 0xffff0000, v193
	s_nop 0
	v_pk_fma_f32 v[152:153], v[164:165], v[152:153], v[70:71]
	s_nop 0
	v_add_co_u32_e64 v118, s[4:5], s96, v174
	v_lshlrev_b32_e32 v70, 16, v141
	s_nop 0
	v_addc_co_u32_e64 v119, s[4:5], 0, v175, s[4:5]
	global_load_dwordx4 v[204:207], v[118:119], off
	v_and_b32_e32 v71, 0xffff0000, v141
	v_lshlrev_b32_e32 v166, 16, v140
	v_and_b32_e32 v167, 0xffff0000, v140
	v_lshlrev_b32_e32 v140, 16, v208
	v_and_b32_e32 v141, 0xffff0000, v208
	v_lshlrev_b32_e32 v68, 16, v209
	v_and_b32_e32 v69, 0xffff0000, v209
	s_waitcnt vmcnt(1)
	v_pk_mul_f32 v[68:69], v[202:203], v[68:69]
	v_pk_mul_f32 v[140:141], v[200:201], v[140:141]
	global_load_dwordx4 v[200:203], v[120:121], off offset:2112
	v_pk_fma_f32 v[68:69], v[74:75], v[166:167], v[68:69]
	v_and_b32_e32 v166, -16, v184
	v_pk_fma_f32 v[140:141], v[72:73], v[70:71], v[140:141]
	v_lshlrev_b32_e32 v162, 16, v117
	v_and_b32_e32 v163, 0xffff0000, v117
	v_lshlrev_b32_e32 v70, 16, v116
	v_and_b32_e32 v71, 0xffff0000, v116
	v_add_u32_e32 v188, s94, v166
	s_waitcnt vmcnt(1)
	v_pk_fma_f32 v[70:71], v[206:207], v[70:71], v[68:69]
	v_pk_fma_f32 v[68:69], v[204:205], v[162:163], v[140:141]
	global_load_dwordx4 v[204:207], v[118:119], off offset:64
	v_lshl_add_u64 v[140:141], v[64:65], 2, v[96:97]
	v_add_u32_e32 v64, 0x2000, v188
	v_cndmask_b32_e32 v187, v180, v64, vcc
	v_add_co_u32_e64 v116, s[4:5], s26, v110
	global_store_dwordx4 v[140:141], v[68:71], off offset:1280
	ds_write_b128 v187, v[68:71] offset:768
	v_addc_co_u32_e64 v117, s[4:5], 0, v111, s[4:5]
	global_load_dwordx4 v[162:165], v[116:117], off offset:2048
	s_nop 0
	s_nop 0
	s_nop 0
	v_lshlrev_b32_e32 v64, 16, v115
	v_and_b32_e32 v65, 0xffff0000, v115
	v_lshlrev_b32_e32 v96, 16, v114
	v_and_b32_e32 v97, 0xffff0000, v114
	v_lshlrev_b32_e32 v114, 16, v210
	v_and_b32_e32 v115, 0xffff0000, v210
	v_lshlrev_b32_e32 v66, 16, v211
	v_and_b32_e32 v67, 0xffff0000, v211
	global_load_dwordx4 v[208:211], v[110:111], off offset:64
	v_add3_u32 v193, s94, v185, v166
	s_waitcnt vmcnt(1)
	v_pk_mul_f32 v[66:67], v[164:165], v[66:67]
	v_pk_mul_f32 v[114:115], v[162:163], v[114:115]
	v_pk_fma_f32 v[66:67], v[78:79], v[96:97], v[66:67]
	v_pk_fma_f32 v[64:65], v[76:77], v[64:65], v[114:115]
	v_lshlrev_b32_e32 v68, 16, v113
	v_and_b32_e32 v69, 0xffff0000, v113
	v_lshlrev_b32_e32 v70, 16, v112
	v_and_b32_e32 v71, 0xffff0000, v112
	v_lshl_add_u64 v[112:113], s[64:65], 0, v[150:151]
	global_load_dwordx4 v[72:75], v[112:113], off
	v_pk_fma_f32 v[70:71], v[86:87], v[70:71], v[66:67]
	v_pk_fma_f32 v[68:69], v[84:85], v[68:69], v[64:65]
	global_load_dwordx4 v[84:87], v[116:117], off offset:2112
	s_nop 0
	ds_write_b128 v193, v[68:71] offset:4096
	v_lshlrev_b32_e32 v162, 16, v144
	v_and_b32_e32 v163, 0xffff0000, v144
	v_lshlrev_b32_e32 v144, 16, v212
	s_waitcnt vmcnt(1)
; #define LAS __attribute__((address_space(3)))
; #define lane LANE_()
; template <int MODE>
; __device__ __forceinline__ void scan_prologue(const ScanP& P, int m0, int seqbase, int T, int h, int d, float* slab, LAS float* lw, float* bon, int lane) {
;     ...
; #pragma unroll
;     for (int n = 0; n < 4; ++n) { const int c = 16 * n + 4 * fq, col = h * 64 + c;
;         k4[n] = CONV3_(pk_, 1);
;         if (MODE != 1) { const f32x4 v4 = CONV3_(pv_, 2); *(f32x4*)(srow + 320 + c) = v4; LAS float* xsel = (fr == (d ? 15 : 0)) ? lw + 2048 + c : lw + 2304 + lane * 4; *(LAS f32x4*)(xsel + 192) = v4; }
;         if (MODE == 2) { r4[n] = CONV3_(pr_, 0); *(LAS f32x4*)(lw + 1024 + fr * 64 + c) = r4[n]; }
;         kk4[n] = k4[n] * *(const f32x4*)(P.k_k + col);
;         ss += (kk4[n].x * kk4[n].x + kk4[n].y * kk4[n].y) + (kk4[n].z * kk4[n].z + kk4[n].w * kk4[n].w); }
	v_pk_mul_f32 v[164:165], v[152:153], v[74:75]
	v_pk_mul_f32 v[166:167], v[154:155], v[72:73]
	v_pk_mul_f32 v[64:65], v[164:165], v[164:165]
	v_pk_mul_f32 v[66:67], v[166:167], v[166:167]
	s_nop 0
	v_pk_mov_b32 v[96:97], v[66:67], v[64:65] op_sel:[1,0]
	v_mov_b32_e32 v67, v65
	v_pk_add_f32 v[114:115], v[96:97], v[66:67]
	v_lshlrev_b32_e32 v96, 16, v145
	v_and_b32_e32 v97, 0xffff0000, v145
	v_and_b32_e32 v145, 0xffff0000, v212
	v_lshlrev_b32_e32 v78, 16, v213
	v_and_b32_e32 v79, 0xffff0000, v213
	v_pk_mul_f32 v[78:79], v[94:95], v[78:79]
	v_pk_mul_f32 v[144:145], v[92:93], v[144:145]
	global_load_dwordx4 v[92:95], v[108:109], off offset:64
	v_pk_fma_f32 v[66:67], v[90:91], v[162:163], v[78:79]
	v_pk_fma_f32 v[64:65], v[88:89], v[96:97], v[144:145]
	global_load_dwordx4 v[88:91], v[112:113], off offset:64
	v_lshlrev_b32_e32 v78, 16, v143
	v_and_b32_e32 v79, 0xffff0000, v143
	v_lshlrev_b32_e32 v96, 16, v142
	v_and_b32_e32 v97, 0xffff0000, v142
	v_pk_fma_f32 v[142:143], v[102:103], v[96:97], v[66:67]
	v_pk_fma_f32 v[144:145], v[100:101], v[78:79], v[64:65]
	global_load_dwordx4 v[100:103], v[110:111], off offset:2176
	v_lshlrev_b32_e32 v78, 16, v157
	v_and_b32_e32 v79, 0xffff0000, v157
	v_lshlrev_b32_e32 v96, 16, v156
	v_and_b32_e32 v97, 0xffff0000, v156
	v_lshlrev_b32_e32 v156, 16, v214
	v_and_b32_e32 v157, 0xffff0000, v214
	v_lshlrev_b32_e32 v74, 16, v215
	v_and_b32_e32 v75, 0xffff0000, v215
	global_load_dwordx4 v[212:215], v[124:125], off offset:128
	v_pk_mul_f32 v[74:75], v[202:203], v[74:75]
	v_pk_mul_f32 v[156:157], v[200:201], v[156:157]
	global_load_dwordx4 v[200:203], v[108:109], off offset:2176
	v_pk_fma_f32 v[66:67], v[106:107], v[96:97], v[74:75]
	v_pk_fma_f32 v[64:65], v[104:105], v[78:79], v[156:157]
	global_load_dwordx4 v[104:107], v[174:175], off offset:128
	v_lshlrev_b32_e32 v74, 16, v147
	v_and_b32_e32 v75, 0xffff0000, v147
	v_lshlrev_b32_e32 v78, 16, v146
	v_and_b32_e32 v79, 0xffff0000, v146
	v_pk_fma_f32 v[64:65], v[204:205], v[74:75], v[64:65]
	v_add_u32_e32 v74, 0x2040, v188
	v_pk_fma_f32 v[66:67], v[206:207], v[78:79], v[66:67]
	v_cndmask_b32_e32 v186, v180, v74, vcc
	global_store_dwordx4 v[140:141], v[64:67], off offset:1344
	ds_write_b128 v186, v[64:67] offset:768
	s_nop 0
	s_nop 0
	s_nop 0
	v_lshlrev_b32_e32 v96, 16, v216
	v_and_b32_e32 v97, 0xffff0000, v216
	v_lshlrev_b32_e32 v72, 16, v217
	v_and_b32_e32 v73, 0xffff0000, v217
	v_lshlrev_b32_e32 v74, 16, v123
	v_and_b32_e32 v75, 0xffff0000, v123
	v_lshlrev_b32_e32 v78, 16, v122
	v_and_b32_e32 v79, 0xffff0000, v122
	v_lshlrev_b32_e32 v146, 16, v158
	v_and_b32_e32 v147, 0xffff0000, v158
	v_lshlrev_b32_e32 v158, 16, v159
	v_and_b32_e32 v159, 0xffff0000, v159
	s_waitcnt vmcnt(7)
	v_pk_mul_f32 v[72:73], v[86:87], v[72:73]
	v_pk_mul_f32 v[96:97], v[84:85], v[96:97]
	global_load_dwordx4 v[84:87], v[120:121], off offset:2176
	v_pk_fma_f32 v[66:67], v[210:211], v[78:79], v[72:73]
	v_pk_fma_f32 v[64:65], v[208:209], v[74:75], v[96:97]
	global_load_dwordx4 v[206:209], v[118:119], off offset:128
	v_lshlrev_b32_e32 v72, 16, v99
	v_and_b32_e32 v73, 0xffff0000, v99
	v_lshlrev_b32_e32 v74, 16, v98
	v_and_b32_e32 v75, 0xffff0000, v98
	s_waitcnt vmcnt(8)
	v_pk_fma_f32 v[66:67], v[94:95], v[74:75], v[66:67]
	v_pk_fma_f32 v[64:65], v[92:93], v[72:73], v[64:65]
	global_load_dwordx4 v[92:95], v[110:111], off offset:128
	s_nop 0
	ds_write_b128 v193, v[64:67] offset:4160
	v_lshlrev_b32_e32 v204, 16, v228
	v_and_b32_e32 v205, 0xffff0000, v228
	v_lshlrev_b32_e32 v76, 16, v229
	v_and_b32_e32 v77, 0xffff0000, v229
	s_waitcnt vmcnt(8)
	v_pk_mul_f32 v[156:157], v[142:143], v[90:91]
	v_pk_mul_f32 v[162:163], v[144:145], v[88:89]
	global_load_dwordx4 v[88:91], v[116:117], off offset:2176
	v_pk_mul_f32 v[72:73], v[156:157], v[156:157]
	v_pk_mul_f32 v[74:75], v[162:163], v[162:163]
	s_nop 0
	v_pk_mov_b32 v[78:79], v[74:75], v[72:73] op_sel:[1,0]
	v_mov_b32_e32 v75, v73
	v_pk_add_f32 v[122:123], v[78:79], v[74:75]
	v_lshlrev_b32_e32 v78, 16, v160
	v_and_b32_e32 v79, 0xffff0000, v160
	v_lshlrev_b32_e32 v160, 16, v161
	v_and_b32_e32 v161, 0xffff0000, v161
	s_waitcnt vmcnt(7)
	v_pk_mul_f32 v[76:77], v[214:215], v[76:77]
	global_load_dwordx4 v[214:217], v[108:109], off offset:128
	v_pk_mul_f32 v[96:97], v[212:213], v[204:205]
	global_load_dwordx4 v[210:213], v[112:113], off offset:128
	v_pk_fma_f32 v[74:75], v[102:103], v[146:147], v[76:77]
	v_pk_fma_f32 v[72:73], v[100:101], v[78:79], v[96:97]
	v_lshlrev_b32_e32 v76, 16, v149
	v_and_b32_e32 v77, 0xffff0000, v149
	v_lshlrev_b32_e32 v78, 16, v148
	v_and_b32_e32 v79, 0xffff0000, v148
	s_waitcnt vmcnt(8)
	v_pk_fma_f32 v[146:147], v[202:203], v[78:79], v[74:75]
	global_load_dwordx4 v[202:205], v[110:111], off offset:2240
	v_pk_fma_f32 v[148:149], v[200:201], v[76:77], v[72:73]
	v_lshlrev_b32_e32 v200, 16, v126
	v_and_b32_e32 v201, 0xffff0000, v126
	v_lshlrev_b32_e32 v126, 16, v127
	v_and_b32_e32 v127, 0xffff0000, v127
	s_waitcnt vmcnt(6)
	v_pk_mul_f32 v[96:97], v[84:85], v[200:201]
	v_pk_mul_f32 v[98:99], v[86:87], v[126:127]
	global_load_dwordx4 v[84:87], v[124:125], off offset:192
	v_pk_fma_f32 v[76:77], v[104:105], v[158:159], v[96:97]
	v_lshlrev_b32_e32 v96, 16, v198
	v_and_b32_e32 v97, 0xffff0000, v198
	global_load_dwordx4 v[198:201], v[108:109], off offset:2240
	v_pk_fma_f32 v[78:79], v[106:107], v[160:161], v[98:99]
	v_lshlrev_b32_e32 v98, 16, v189
	v_and_b32_e32 v99, 0xffff0000, v189
	s_waitcnt vmcnt(7)
; #define LAS __attribute__((address_space(3)))
; __device__ __forceinline__ float shx(float v, int o, int lane) { return __builtin_bit_cast(float, __builtin_amdgcn_ds_bpermute((lane ^ o) << 2, __builtin_bit_cast(int, v))); }
; #define lane LANE_()
; template <int MODE>
; __device__ __forceinline__ void scan_prologue(const ScanP& P, int m0, int seqbase, int T, int h, int d, float* slab, LAS float* lw, float* bon, int lane) {
;     ...
; #pragma unroll
;     for (int n = 0; n < 4; ++n) { const int c = 16 * n + 4 * fq, col = h * 64 + c;
;         k4[n] = CONV3_(pk_, 1);
;         if (MODE != 1) { const f32x4 v4 = CONV3_(pv_, 2); *(f32x4*)(srow + 320 + c) = v4; LAS float* xsel = (fr == (d ? 15 : 0)) ? lw + 2048 + c : lw + 2304 + lane * 4; *(LAS f32x4*)(xsel + 192) = v4; }
;         if (MODE == 2) { r4[n] = CONV3_(pr_, 0); *(LAS f32x4*)(lw + 1024 + fr * 64 + c) = r4[n]; }
;         kk4[n] = k4[n] * *(const f32x4*)(P.k_k + col);
;         ss += (kk4[n].x * kk4[n].x + kk4[n].y * kk4[n].y) + (kk4[n].z * kk4[n].z + kk4[n].w * kk4[n].w); }
;     ...
;     ss += shx(ss, 16, lane); ss += shx(ss, 32, lane);
;     const float rs = __builtin_amdgcn_rsqf(ss + 1e-12f);
	v_pk_fma_f32 v[72:73], v[206:207], v[96:97], v[76:77]
	v_add_u32_e32 v76, 0x2080, v188
	v_pk_fma_f32 v[74:75], v[208:209], v[98:99], v[78:79]
	global_load_dwordx4 v[206:209], v[174:175], off offset:192
	v_cndmask_b32_e32 v189, v180, v76, vcc
	global_store_dwordx4 v[140:141], v[72:75], off offset:1408
	ds_write_b128 v189, v[72:75] offset:768
	s_nop 0
	s_nop 0
	s_nop 0
	v_lshlrev_b32_e32 v160, 16, v230
	v_and_b32_e32 v161, 0xffff0000, v230
	v_lshlrev_b32_e32 v100, 16, v231
	v_and_b32_e32 v101, 0xffff0000, v231
	global_load_dwordx4 v[228:231], v[120:121], off offset:2240
	v_lshlrev_b32_e32 v126, 16, v173
	v_and_b32_e32 v127, 0xffff0000, v173
	v_lshlrev_b32_e32 v158, 16, v172
	v_and_b32_e32 v159, 0xffff0000, v172
	s_waitcnt vmcnt(8)
	v_pk_mul_f32 v[78:79], v[90:91], v[100:101]
	v_pk_mul_f32 v[76:77], v[88:89], v[160:161]
	global_load_dwordx4 v[88:91], v[118:119], off offset:192
	v_pk_fma_f32 v[74:75], v[94:95], v[158:159], v[78:79]
	v_pk_fma_f32 v[72:73], v[92:93], v[126:127], v[76:77]
	global_load_dwordx4 v[92:95], v[110:111], off offset:192
	v_lshlrev_b32_e32 v76, 16, v169
	v_and_b32_e32 v77, 0xffff0000, v169
	v_lshlrev_b32_e32 v78, 16, v168
	v_and_b32_e32 v79, 0xffff0000, v168
	s_waitcnt vmcnt(9)
	v_pk_fma_f32 v[78:79], v[216:217], v[78:79], v[74:75]
	v_pk_fma_f32 v[76:77], v[214:215], v[76:77], v[72:73]
	global_load_dwordx4 v[214:217], v[116:117], off offset:2240
	s_nop 0
	ds_write_b128 v193, v[76:79] offset:4224
	v_lshlrev_b32_e32 v160, 16, v232
	v_and_b32_e32 v161, 0xffff0000, v232
	v_lshlrev_b32_e32 v102, 16, v233
	v_and_b32_e32 v103, 0xffff0000, v233
	v_lshlrev_b32_e32 v100, 16, v195
	v_and_b32_e32 v101, 0xffff0000, v195
	v_lshlrev_b32_e32 v158, 16, v194
	v_and_b32_e32 v159, 0xffff0000, v194
	s_waitcnt vmcnt(9)
	v_pk_mul_f32 v[168:169], v[146:147], v[212:213]
	v_pk_mul_f32 v[172:173], v[148:149], v[210:211]
	global_load_dwordx4 v[210:213], v[108:109], off offset:192
	s_nop 0
	s_nop 0
	s_nop 0
	s_nop 0
	s_waitcnt vmcnt(8)
	v_pk_mul_f32 v[98:99], v[86:87], v[102:103]
	v_pk_mul_f32 v[96:97], v[84:85], v[160:161]
	global_load_dwordx4 v[84:87], v[112:113], off offset:192
	v_pk_fma_f32 v[74:75], v[204:205], v[158:159], v[98:99]
	v_pk_fma_f32 v[72:73], v[202:203], v[100:101], v[96:97]
	v_lshlrev_b32_e32 v96, 16, v197
	v_and_b32_e32 v97, 0xffff0000, v197
	v_lshlrev_b32_e32 v98, 16, v196
	v_and_b32_e32 v99, 0xffff0000, v196
	s_waitcnt vmcnt(8)
	v_pk_fma_f32 v[158:159], v[200:201], v[98:99], v[74:75]
	v_pk_fma_f32 v[160:161], v[198:199], v[96:97], v[72:73]
	v_lshlrev_b32_e32 v124, 16, v234
	v_and_b32_e32 v125, 0xffff0000, v234
	v_lshlrev_b32_e32 v118, 16, v192
	v_and_b32_e32 v119, 0xffff0000, v192
	v_lshlrev_b32_e32 v106, 16, v235
	v_and_b32_e32 v107, 0xffff0000, v235
	v_lshlrev_b32_e32 v120, 16, v191
	v_and_b32_e32 v121, 0xffff0000, v191
	s_waitcnt vmcnt(5)
	v_pk_mul_f32 v[96:97], v[228:229], v[124:125]
	v_pk_mul_f32 v[98:99], v[230:231], v[106:107]
	v_pk_fma_f32 v[72:73], v[206:207], v[118:119], v[96:97]
	v_lshlrev_b32_e32 v96, 16, v182
	v_and_b32_e32 v97, 0xffff0000, v182
	v_pk_fma_f32 v[74:75], v[208:209], v[120:121], v[98:99]
	v_lshlrev_b32_e32 v98, 16, v179
	v_and_b32_e32 v99, 0xffff0000, v179
	s_waitcnt vmcnt(4)
	v_pk_fma_f32 v[72:73], v[88:89], v[96:97], v[72:73]
	v_add_u32_e32 v96, 0x20c0, v188
	v_pk_fma_f32 v[74:75], v[90:91], v[98:99], v[74:75]
	v_cndmask_b32_e32 v192, v180, v96, vcc
	global_store_dwordx4 v[140:141], v[72:75], off offset:1472
	ds_write_b128 v192, v[72:75] offset:768
	s_nop 0
	s_nop 0
	s_nop 0
	v_lshlrev_b32_e32 v110, 16, v236
	v_and_b32_e32 v111, 0xffff0000, v236
	v_lshlrev_b32_e32 v104, 16, v237
	v_and_b32_e32 v105, 0xffff0000, v237
	v_lshlrev_b32_e32 v106, 16, v177
	v_and_b32_e32 v107, 0xffff0000, v177
	v_lshlrev_b32_e32 v108, 16, v176
	v_and_b32_e32 v109, 0xffff0000, v176
	v_lshl_or_b32 v180, v178, 6, s49
	v_or_b32_e32 v120, 0xc00, v180
	v_mov_b32_e32 v121, v181
	v_lshl_add_u64 v[120:121], v[120:121], 0, v[170:171]
	v_lshlrev_b64 v[124:125], 1, v[120:121]
	v_lshl_add_u64 v[120:121], s[76:77], 0, v[124:125]
	global_load_dwordx4 v[194:197], v[120:121], off
	v_cmp_gt_u32_e32 vcc, 16, v184
	s_waitcnt vmcnt(4)
	v_pk_mul_f32 v[98:99], v[216:217], v[104:105]
	v_pk_mul_f32 v[96:97], v[214:215], v[110:111]
	v_pk_fma_f32 v[74:75], v[94:95], v[108:109], v[98:99]
	v_pk_fma_f32 v[72:73], v[92:93], v[106:107], v[96:97]
	v_lshlrev_b32_e32 v96, 16, v190
	v_and_b32_e32 v97, 0xffff0000, v190
	v_lshlrev_b32_e32 v98, 16, v183
	v_and_b32_e32 v99, 0xffff0000, v183
	s_waitcnt vmcnt(3)
	v_pk_fma_f32 v[74:75], v[212:213], v[98:99], v[74:75]
	v_pk_fma_f32 v[72:73], v[210:211], v[96:97], v[72:73]
	s_nop 0
	ds_write_b128 v193, v[72:75] offset:4288
	v_or_b32_e32 v112, 0x800, v180
	v_mov_b32_e32 v113, v181
	v_lshl_add_u64 v[112:113], v[112:113], 0, v[170:171]
	v_lshlrev_b64 v[116:117], 1, v[112:113]
	v_lshl_add_u64 v[112:113], s[76:77], 0, v[116:117]
	global_load_dwordx4 v[88:91], v[112:113], off
	v_lshl_add_u64 v[116:117], s[78:79], 0, v[116:117]
	global_load_dwordx4 v[116:119], v[116:117], off
	s_waitcnt vmcnt(4)
	v_pk_mul_f32 v[176:177], v[160:161], v[84:85]
	v_pk_mul_f32 v[174:175], v[158:159], v[86:87]
	v_mul_f32_e32 v98, v176, v176
	v_pk_add_f32 v[96:97], v[114:115], v[114:115] op_sel:[0,1] op_sel_hi:[1,0]
	v_mul_f32_e32 v100, v177, v177
	v_mov_b32_e32 v97, v98
	v_pk_add_f32 v[98:99], v[122:123], v[122:123] op_sel:[0,1] op_sel_hi:[1,0]
	v_mul_f32_e32 v101, v174, v174
	v_mov_b32_e32 v99, v100
	v_pk_add_f32 v[96:97], v[96:97], v[98:99]
	v_mul_f32_e32 v98, v173, v173
	v_pk_fma_f32 v[98:99], v[172:173], v[172:173], v[98:99] op_sel_hi:[1,1,0]
	v_mul_f32_e32 v100, v169, v169
	v_mul_f32_e32 v102, v175, v175
	v_mov_b32_e32 v99, v101
	v_pk_fma_f32 v[100:101], v[168:169], v[168:169], v[100:101] op_sel_hi:[1,1,0]
	v_mov_b32_e32 v101, v102
	v_pk_add_f32 v[98:99], v[98:99], v[100:101]
	s_nop 0
	v_pk_add_f32 v[96:97], v[96:97], v[98:99]
	s_nop 0
	v_add_f32_e32 v96, v96, v97
	v_lshlrev_b32_e32 v97, 2, v184
	v_xor_b32_e32 v191, 64, v97
	ds_bpermute_b32 v98, v191, v96
	v_xor_b32_e32 v190, 0x80, v97
	s_waitcnt lgkmcnt(0)
; __device__ __forceinline__ unsigned pk2(float lo, float hi) { const f2 v = {lo, hi}; return __builtin_bit_cast(unsigned, __builtin_convertvector(v, bf16x2_hw)); }
; __device__ __forceinline__ float tanhf_(float x) { return 1.0f - 2.0f * __builtin_amdgcn_rcpf(1.0f + __builtin_amdgcn_exp2f(2.8853900817779268f * x)); }
; __device__ __forceinline__ float shx(float v, int o, int lane) { return __builtin_bit_cast(float, __builtin_amdgcn_ds_bpermute((lane ^ o) << 2, __builtin_bit_cast(int, v))); }
; #define lane LANE_()
; template <int MODE>
; __device__ __forceinline__ void scan_prologue(const ScanP& P, int m0, int seqbase, int T, int h, int d, float* slab, LAS float* lw, float* bon, int lane) {
;     ...
;     ss += shx(ss, 16, lane); ss += shx(ss, 32, lane);
;     const float rs = __builtin_amdgcn_rsqf(ss + 1e-12f);
;     f32x4 Dw[4], Da[4];
; #pragma unroll
;     for (int n = 0; n < 4; ++n) { Dw[n] = (f32x4){0.f, 0.f, 0.f, 0.f}; Da[n] = (f32x4){0.f, 0.f, 0.f, 0.f}; }
; #pragma unroll
;     for (int ks = 0; ks < 2; ++ks) {
;         const v4u xw = xw_[ks]; const bf16x8 xa = xa_[ks];
;         v4u tw;
; #pragma unroll
;         for (int e = 0; e < 4; ++e) tw[e] = pk2(tanhf_(bflo(xw[e])), tanhf_(bfhi(xw[e])));
;         const bf16x8 twv = __builtin_bit_cast(bf16x8, tw);
; #pragma unroll
;         for (int n = 0; n < 4; ++n) { const size_t wo = (size_t)(h * 64 + 16 * n + fr) * 64 + ks * 32 + 8 * fq;
;             Dw[n] = __builtin_amdgcn_mfma_f32_16x16x32_bf16(*(const bf16x8*)(P.upw + wo), twv, Dw[n], 0, 0, 0);
;             Da[n] = __builtin_amdgcn_mfma_f32_16x16x32_bf16(*(const bf16x8*)(P.upa + wo), xa, Da[n], 0, 0, 0); }
;     }
	v_add_f32_e32 v96, v96, v98
	ds_bpermute_b32 v97, v190, v96
	s_waitcnt lgkmcnt(0)
	v_add_f32_e32 v96, v96, v97
	v_add_f32_e32 v193, 0x2b8cbccc, v96
	v_lshlrev_b32_e32 v96, 16, v238
	v_and_b32_e32 v92, 0xffff0000, v238
	v_mul_f32_e32 v92, 0x4038aa3b, v92
	v_exp_f32_e32 v92, v92
	v_mul_f32_e32 v96, 0x4038aa3b, v96
	v_exp_f32_e32 v96, v96
	v_add_f32_e32 v92, 1.0, v92
	v_rcp_f32_e32 v97, v92
	v_lshlrev_b32_e32 v92, 16, v239
	v_and_b32_e32 v93, 0xffff0000, v239
	v_mul_f32_e32 v92, 0x4038aa3b, v92
	v_mul_f32_e32 v93, 0x4038aa3b, v93
	v_exp_f32_e32 v92, v92
	v_exp_f32_e32 v93, v93
	v_add_f32_e32 v96, 1.0, v96
	v_rcp_f32_e32 v96, v96
	v_add_f32_e32 v92, 1.0, v92
	v_add_f32_e32 v93, 1.0, v93
	v_rcp_f32_e32 v92, v92
	v_rcp_f32_e32 v93, v93
	v_pk_fma_f32 v[96:97], v[96:97], 2.0, 1.0 op_sel_hi:[1,0,0] neg_lo:[1,0,0] neg_hi:[1,0,0]
	v_pk_fma_f32 v[92:93], v[92:93], 2.0, 1.0 op_sel_hi:[1,0,0] neg_lo:[1,0,0] neg_hi:[1,0,0]
	s_nop 0
	v_cvt_pk_bf16_f32 v105, v92, v93
	v_lshlrev_b32_e32 v92, 16, v240
	v_and_b32_e32 v93, 0xffff0000, v240
	v_mul_f32_e32 v92, 0x4038aa3b, v92
	v_mul_f32_e32 v93, 0x4038aa3b, v93
	v_exp_f32_e32 v92, v92
	v_exp_f32_e32 v93, v93
	v_cvt_pk_bf16_f32 v104, v96, v97
	v_add_f32_e32 v92, 1.0, v92
	v_add_f32_e32 v93, 1.0, v93
	v_rcp_f32_e32 v92, v92
	v_rcp_f32_e32 v93, v93
	s_nop 0
	v_pk_fma_f32 v[92:93], v[92:93], 2.0, 1.0 op_sel_hi:[1,0,0] neg_lo:[1,0,0] neg_hi:[1,0,0]
	s_nop 0
	v_cvt_pk_bf16_f32 v106, v92, v93
	v_lshlrev_b32_e32 v92, 16, v241
	v_and_b32_e32 v93, 0xffff0000, v241
	v_mul_f32_e32 v92, 0x4038aa3b, v92
	v_mul_f32_e32 v93, 0x4038aa3b, v93
	v_exp_f32_e32 v92, v92
	v_exp_f32_e32 v93, v93
	v_add_f32_e32 v92, 1.0, v92
	v_add_f32_e32 v93, 1.0, v93
	v_rcp_f32_e32 v92, v92
	v_rcp_f32_e32 v93, v93
	s_nop 0
	v_pk_fma_f32 v[92:93], v[92:93], 2.0, 1.0 op_sel_hi:[1,0,0] neg_lo:[1,0,0] neg_hi:[1,0,0]
	s_nop 0
	v_cvt_pk_bf16_f32 v107, v92, v93
	v_lshl_add_u64 v[92:93], v[180:181], 0, v[170:171]
	v_lshlrev_b64 v[96:97], 1, v[92:93]
	v_lshl_add_u64 v[178:179], s[76:77], 0, v[96:97]
	global_load_dwordx4 v[84:87], v[178:179], off offset:2048
	global_load_dwordx4 v[202:205], v[178:179], off offset:64
	global_load_dwordx4 v[210:213], v[178:179], off offset:2112
	global_load_dwordx4 v[92:95], v[178:179], off
	v_lshl_add_u64 v[182:183], s[78:79], 0, v[96:97]
	global_load_dwordx4 v[198:201], v[182:183], off
	global_load_dwordx4 v[100:103], v[182:183], off offset:2048
	global_load_dwordx4 v[206:209], v[182:183], off offset:64
	global_load_dwordx4 v[214:217], v[182:183], off offset:2112
	s_nop 0
	s_waitcnt vmcnt(4)
	v_mfma_f32_16x16x32_bf16 v[108:111], v[92:95], v[104:107], 0
	s_nop 0
	s_nop 0
	v_mfma_f32_16x16x32_bf16 v[96:99], v[84:87], v[104:107], 0
	v_mfma_f32_16x16x32_bf16 v[112:115], v[88:91], v[104:107], 0
	v_mfma_f32_16x16x32_bf16 v[120:123], v[194:197], v[104:107], 0
	v_lshl_add_u64 v[104:105], s[78:79], 0, v[124:125]
	global_load_dwordx4 v[104:107], v[104:105], off
	s_waitcnt vmcnt(4)
	v_mfma_f32_16x16x32_bf16 v[92:95], v[198:201], v[242:245], 0
	s_waitcnt vmcnt(3)
	v_mfma_f32_16x16x32_bf16 v[100:103], v[100:103], v[242:245], 0
	v_mfma_f32_16x16x32_bf16 v[116:119], v[116:119], v[242:245], 0
	s_waitcnt vmcnt(0)
	v_mfma_f32_16x16x32_bf16 v[124:127], v[104:107], v[242:245], 0
	v_lshlrev_b32_e32 v88, 16, v246
	v_and_b32_e32 v84, 0xffff0000, v246
	v_mul_f32_e32 v88, 0x4038aa3b, v88
	v_mul_f32_e32 v84, 0x4038aa3b, v84
	v_exp_f32_e32 v88, v88
	v_exp_f32_e32 v84, v84
	v_add_f32_e32 v88, 1.0, v88
	v_add_f32_e32 v84, 1.0, v84
	v_rcp_f32_e32 v88, v88
	v_rcp_f32_e32 v89, v84
	s_nop 0
	v_pk_fma_f32 v[88:89], v[88:89], 2.0, 1.0 op_sel_hi:[1,0,0] neg_lo:[1,0,0] neg_hi:[1,0,0]
	s_nop 0
	v_cvt_pk_bf16_f32 v84, v88, v89
	v_lshlrev_b32_e32 v88, 16, v247
	v_and_b32_e32 v85, 0xffff0000, v247
	v_mul_f32_e32 v88, 0x4038aa3b, v88
	v_mul_f32_e32 v85, 0x4038aa3b, v85
	v_exp_f32_e32 v88, v88
	v_exp_f32_e32 v85, v85
	v_add_f32_e32 v88, 1.0, v88
	v_add_f32_e32 v85, 1.0, v85
	v_rcp_f32_e32 v88, v88
	v_rcp_f32_e32 v89, v85
	s_nop 0
	v_pk_fma_f32 v[88:89], v[88:89], 2.0, 1.0 op_sel_hi:[1,0,0] neg_lo:[1,0,0] neg_hi:[1,0,0]
	s_nop 0
	v_cvt_pk_bf16_f32 v85, v88, v89
	v_lshlrev_b32_e32 v88, 16, v248
	v_and_b32_e32 v86, 0xffff0000, v248
	v_mul_f32_e32 v88, 0x4038aa3b, v88
	v_mul_f32_e32 v86, 0x4038aa3b, v86
	v_exp_f32_e32 v88, v88
	v_exp_f32_e32 v86, v86
	v_add_f32_e32 v88, 1.0, v88
	v_add_f32_e32 v86, 1.0, v86
	v_rcp_f32_e32 v88, v88
	v_rcp_f32_e32 v89, v86
	s_nop 0
	v_pk_fma_f32 v[88:89], v[88:89], 2.0, 1.0 op_sel_hi:[1,0,0] neg_lo:[1,0,0] neg_hi:[1,0,0]
	s_nop 0
	v_cvt_pk_bf16_f32 v86, v88, v89
	v_lshlrev_b32_e32 v88, 16, v249
	v_and_b32_e32 v87, 0xffff0000, v249
	v_mul_f32_e32 v88, 0x4038aa3b, v88
	v_mul_f32_e32 v87, 0x4038aa3b, v87
	v_exp_f32_e32 v88, v88
	v_exp_f32_e32 v87, v87
	v_add_f32_e32 v88, 1.0, v88
	v_add_f32_e32 v87, 1.0, v87
	v_rcp_f32_e32 v88, v88
	v_rcp_f32_e32 v89, v87
	s_nop 0
	v_pk_fma_f32 v[88:89], v[88:89], 2.0, 1.0 op_sel_hi:[1,0,0] neg_lo:[1,0,0] neg_hi:[1,0,0]
	s_nop 0
	v_cvt_pk_bf16_f32 v87, v88, v89
	s_nop 0
	v_mfma_f32_16x16x32_bf16 v[104:107], v[202:205], v[84:87], v[108:111]
	s_nop 0
	v_mfma_f32_16x16x32_bf16 v[108:111], v[206:209], v[80:83], v[92:95]
	s_nop 0
	v_lshl_add_u64 v[178:179], s[66:67], 0, v[150:151]
	global_load_dwordx4 v[198:201], v[178:179], off
	global_load_dwordx4 v[202:205], v[178:179], off offset:64
	global_load_dwordx4 v[232:235], v[178:179], off offset:128
	global_load_dwordx4 v[236:239], v[178:179], off offset:192
	v_mfma_f32_16x16x32_bf16 v[96:99], v[210:213], v[84:87], v[96:99]
	s_nop 0
	v_mfma_f32_16x16x32_bf16 v[100:103], v[214:217], v[80:83], v[100:103]
	v_or_b32_e32 v88, 0x820, v180
	v_mov_b32_e32 v89, v181
	v_lshl_add_u64 v[88:89], v[88:89], 0, v[170:171]
	v_lshlrev_b64 v[92:93], 1, v[88:89]
	v_lshl_add_u64 v[88:89], s[76:77], 0, v[92:93]
	global_load_dwordx4 v[88:91], v[88:89], off
	v_lshl_add_u64 v[92:93], s[78:79], 0, v[92:93]
	global_load_dwordx4 v[92:95], v[92:93], off
	v_or_b32_e32 v180, 0xc20, v180
	s_waitcnt vmcnt(1)
; #define LAS __attribute__((address_space(3)))
; __device__ __forceinline__ float sigmoidf_(float x) { return __builtin_amdgcn_rcpf(1.0f + __builtin_amdgcn_exp2f(-1.4426950408889634f * x)); }
; #define lane LANE_()
; template <int MODE>
; __device__ __forceinline__ void scan_prologue(const ScanP& P, int m0, int seqbase, int T, int h, int d, float* slab, LAS float* lw, float* bon, int lane) {
;     ...
;         for (int n = 0; n < 4; ++n) { const size_t wo = (size_t)(h * 64 + 16 * n + fr) * 64 + ks * 32 + 8 * fq;
;             Dw[n] = __builtin_amdgcn_mfma_f32_16x16x32_bf16(*(const bf16x8*)(P.upw + wo), twv, Dw[n], 0, 0, 0);
;             Da[n] = __builtin_amdgcn_mfma_f32_16x16x32_bf16(*(const bf16x8*)(P.upa + wo), xa, Da[n], 0, 0, 0); }
;     }
;     float bp = 0.f;
; #pragma unroll
;     for (int n = 0; n < 4; ++n) { const int c = 16 * n + 4 * fq, col = h * 64 + c;
;         const f32x4 w0 = *(const f32x4*)(P.w0 + col), a0 = *(const f32x4*)(P.a0 + col), ka = *(const f32x4*)(P.k_a + col);
;         f32x4 wv, bv, kd, av;
; #pragma unroll
;         for (int i = 0; i < 4; ++i) { const float ic = sigmoidf_(Da[n][i] + a0[i]);
;             wv[i] = __builtin_amdgcn_exp2f(-DECAY_SCALE * 1.4426950408889634f * sigmoidf_(Dw[n][i] + w0[i]));
;             const float kk = kk4[n][i] * rs; av[i] = -kk; bv[i] = kk * ic; kd[i] = k4[n][i] * (1.0f + (ic - 1.0f) * ka[i]); }
;         *(LAS f32x4*)(lw + fr * 64 + c) = av; *(LAS f32x4*)(lw + 3072 + fr * 64 + c) = wv; *(LAS f32x4*)(lw + (MODE == 3 ? 1024 : 4096) + fr * 64 + c) = bv;
;         if (MODE != 1) *(f32x4*)(srow + 192 + c) = kd;
;         { LAS float* xsel = (fr == (d ? 15 : 0)) ? lw + 2048 + c : lw + 2304 + lane * 4;
;           if (MODE != 1) *(LAS f32x4*)(xsel + 128) = kd; }
;         if (MODE == 2) { const f32x4 rk = *(const f32x4*)(P.r_k + col); const f32x4 t = r4[n] * kd * rk; bp += (t.x + t.y) + (t.z + t.w); }
;         if ((n & 1) == 1) asm volatile("" ::: "memory");
;     }
	v_mfma_f32_16x16x32_bf16 v[88:91], v[88:91], v[84:87], v[112:115]
	s_nop 2
	v_lshl_add_u64 v[112:113], v[180:181], 0, v[170:171]
	v_lshl_add_u64 v[170:171], s[74:75], 0, v[150:151]
	global_load_dwordx4 v[194:197], v[170:171], off
	global_load_dwordx4 v[206:209], v[170:171], off offset:64
	global_load_dwordx4 v[228:231], v[170:171], off offset:128
	global_load_dwordx4 v[240:243], v[170:171], off offset:192
	s_waitcnt vmcnt(4)
	v_mfma_f32_16x16x32_bf16 v[92:95], v[92:95], v[80:83], v[116:119]
	s_nop 2
	v_lshlrev_b64 v[116:117], 1, v[112:113]
	v_lshl_add_u64 v[112:113], s[76:77], 0, v[116:117]
	global_load_dwordx4 v[112:115], v[112:113], off
	s_waitcnt vmcnt(0)
	v_mfma_f32_16x16x32_bf16 v[84:87], v[112:115], v[84:87], v[120:123]
	v_lshl_add_u64 v[112:113], s[78:79], 0, v[116:117]
	global_load_dwordx4 v[112:115], v[112:113], off
	s_nop 0
	s_nop 0
	s_waitcnt vmcnt(0)
	v_mfma_f32_16x16x32_bf16 v[80:83], v[112:115], v[80:83], v[124:127]
	s_nop 2
	v_lshl_add_u64 v[126:127], s[72:73], 0, v[150:151]
	global_load_dwordx4 v[210:213], v[126:127], off offset:64
	global_load_dwordx4 v[214:217], v[126:127], off offset:128
	global_load_dwordx4 v[244:247], v[126:127], off offset:192
	global_load_dwordx4 v[112:115], v[126:127], off
	s_nop 0
	v_add_f32_e32 v108, v108, v194
	v_add_f32_e32 v110, v110, v196
	v_mul_f32_e32 v108, 0xbfb8aa3b, v108
	v_mul_f32_e32 v110, 0xbfb8aa3b, v110
	v_exp_f32_e32 v108, v108
	v_exp_f32_e32 v110, v110
	v_rsq_f32_e32 v124, v193
	v_add_f32_e32 v108, 1.0, v108
	v_add_f32_e32 v110, 1.0, v110
	v_rcp_f32_e32 v182, v108
	v_add_f32_e32 v108, v109, v195
	v_mul_f32_e32 v108, 0xbfb8aa3b, v108
	v_exp_f32_e32 v108, v108
	s_waitcnt vmcnt(0)
	v_add_f32_e32 v104, v104, v112
	v_add_f32_e32 v105, v105, v113
	v_add_f32_e32 v106, v106, v114
	v_add_f32_e32 v107, v107, v115
	v_mul_f32_e32 v104, 0xbfb8aa3b, v104
	v_mul_f32_e32 v105, 0xbfb8aa3b, v105
	v_pk_mul_f32 v[112:113], v[166:167], v[124:125] op_sel_hi:[1,0]
	v_rcp_f32_e32 v166, v110
	v_mul_f32_e32 v106, 0xbfb8aa3b, v106
	v_add_f32_e32 v110, v111, v197
	v_mul_f32_e32 v107, 0xbfb8aa3b, v107
	v_exp_f32_e32 v104, v104
	v_exp_f32_e32 v105, v105
	v_exp_f32_e32 v106, v106
	v_mul_f32_e32 v110, 0xbfb8aa3b, v110
	v_exp_f32_e32 v107, v107
	v_exp_f32_e32 v110, v110
	v_add_f32_e32 v104, 1.0, v104
	v_add_f32_e32 v105, 1.0, v105
	v_add_f32_e32 v106, 1.0, v106
	v_add_f32_e32 v107, 1.0, v107
	v_rcp_f32_e32 v104, v104
	v_add_f32_e32 v108, 1.0, v108
	v_rcp_f32_e32 v105, v105
	v_rcp_f32_e32 v106, v106
	v_add_f32_e32 v110, 1.0, v110
	v_rcp_f32_e32 v107, v107
	v_rcp_f32_e32 v183, v108
	v_rcp_f32_e32 v167, v110
	v_mul_f32_e32 v104, 0xbf60028a, v104
	v_mul_f32_e32 v105, 0xbf60028a, v105
	v_mul_f32_e32 v106, 0xbf60028a, v106
	v_mul_f32_e32 v107, 0xbf60028a, v107
	v_pk_mul_f32 v[114:115], v[164:165], v[124:125] op_sel_hi:[1,0]
	v_exp_f32_e32 v104, v104
	v_exp_f32_e32 v105, v105
	v_xor_b32_e32 v109, 0x80000000, v113
	v_xor_b32_e32 v108, 0x80000000, v112
	v_exp_f32_e32 v106, v106
	v_exp_f32_e32 v107, v107
	v_xor_b32_e32 v110, 0x80000000, v114
	v_xor_b32_e32 v111, 0x80000000, v115
	v_pk_mul_f32 v[116:117], v[112:113], v[182:183]
	v_pk_mul_f32 v[118:119], v[114:115], v[166:167]
	v_pk_add_f32 v[112:113], v[166:167], -1.0 op_sel_hi:[1,0]
	v_pk_add_f32 v[114:115], v[182:183], -1.0 op_sel_hi:[1,0]
	v_pk_fma_f32 v[112:113], v[200:201], v[112:113], 1.0 op_sel_hi:[1,1,0]
	v_pk_fma_f32 v[114:115], v[198:199], v[114:115], 1.0 op_sel_hi:[1,1,0]
	v_pk_mul_f32 v[122:123], v[152:153], v[112:113]
	v_pk_mul_f32 v[120:121], v[154:155], v[114:115]
	v_add_u32_e32 v114, v188, v185
	ds_write_b128 v114, v[108:111]
	ds_write_b128 v114, v[104:107] offset:12288
	ds_write_b128 v114, v[116:119] offset:16384
	global_store_dwordx4 v[140:141], v[120:123], off offset:768
	v_lshl_add_u64 v[112:113], s[68:69], 0, v[150:151]
	global_load_dwordx4 v[116:119], v[112:113], off offset:64
	global_load_dwordx4 v[150:153], v[112:113], off offset:128
	global_load_dwordx4 v[164:167], v[112:113], off offset:192
	global_load_dwordx4 v[104:107], v[112:113], off
	v_pk_mul_f32 v[70:71], v[70:71], v[122:123]
	v_pk_mul_f32 v[68:69], v[68:69], v[120:121]
	ds_write_b128 v187, v[120:123] offset:512
	s_waitcnt vmcnt(0)
	v_pk_mul_f32 v[70:71], v[106:107], v[70:71]
	v_pk_mul_f32 v[68:69], v[104:105], v[68:69]
	s_nop 0
	v_add_f32_e32 v68, v68, v69
	v_add_f32_e32 v69, v70, v71
	v_add_f32_e32 v68, v68, v69
	v_add_f32_e32 v115, 0, v68
	v_add_f32_e32 v100, v100, v206
	v_add_f32_e32 v96, v96, v210
	v_add_f32_e32 v97, v97, v211
	v_add_f32_e32 v98, v98, v212
	v_add_f32_e32 v99, v99, v213
	v_mul_f32_e32 v96, 0xbfb8aa3b, v96
	v_add_f32_e32 v101, v101, v207
	v_mul_f32_e32 v97, 0xbfb8aa3b, v97
	v_add_f32_e32 v102, v102, v208
	v_mul_f32_e32 v98, 0xbfb8aa3b, v98
	v_add_f32_e32 v103, v103, v209
	v_mul_f32_e32 v99, 0xbfb8aa3b, v99
	v_mul_f32_e32 v100, 0xbfb8aa3b, v100
	v_exp_f32_e32 v96, v96
	v_mul_f32_e32 v101, 0xbfb8aa3b, v101
	v_exp_f32_e32 v97, v97
	v_mul_f32_e32 v102, 0xbfb8aa3b, v102
	v_exp_f32_e32 v98, v98
	v_mul_f32_e32 v103, 0xbfb8aa3b, v103
	v_exp_f32_e32 v99, v99
	v_exp_f32_e32 v100, v100
	v_exp_f32_e32 v101, v101
	v_exp_f32_e32 v102, v102
	v_exp_f32_e32 v103, v103
	v_add_f32_e32 v96, 1.0, v96
	v_add_f32_e32 v97, 1.0, v97
	v_add_f32_e32 v98, 1.0, v98
	v_add_f32_e32 v99, 1.0, v99
	v_add_f32_e32 v100, 1.0, v100
	v_rcp_f32_e32 v96, v96
	v_add_f32_e32 v101, 1.0, v101
	v_rcp_f32_e32 v97, v97
	v_add_f32_e32 v102, 1.0, v102
	v_rcp_f32_e32 v98, v98
	v_add_f32_e32 v103, 1.0, v103
	v_rcp_f32_e32 v99, v99
	v_rcp_f32_e32 v100, v100
	v_rcp_f32_e32 v101, v101
	v_rcp_f32_e32 v102, v102
	v_rcp_f32_e32 v103, v103
	v_mul_f32_e32 v96, 0xbf60028a, v96
	v_mul_f32_e32 v97, 0xbf60028a, v97
; #define LAS __attribute__((address_space(3)))
; __device__ __forceinline__ float sigmoidf_(float x) { return __builtin_amdgcn_rcpf(1.0f + __builtin_amdgcn_exp2f(-1.4426950408889634f * x)); }
; __device__ __forceinline__ float shx(float v, int o, int lane) { return __builtin_bit_cast(float, __builtin_amdgcn_ds_bpermute((lane ^ o) << 2, __builtin_bit_cast(int, v))); }
; #define lane LANE_()
; template <int MODE>
; __device__ __forceinline__ void scan_prologue(const ScanP& P, int m0, int seqbase, int T, int h, int d, float* slab, LAS float* lw, float* bon, int lane) {
;     ...
;     for (int n = 0; n < 4; ++n) { const int c = 16 * n + 4 * fq, col = h * 64 + c;
;         const f32x4 w0 = *(const f32x4*)(P.w0 + col), a0 = *(const f32x4*)(P.a0 + col), ka = *(const f32x4*)(P.k_a + col);
;         f32x4 wv, bv, kd, av;
; #pragma unroll
;         for (int i = 0; i < 4; ++i) { const float ic = sigmoidf_(Da[n][i] + a0[i]);
;             wv[i] = __builtin_amdgcn_exp2f(-DECAY_SCALE * 1.4426950408889634f * sigmoidf_(Dw[n][i] + w0[i]));
;             const float kk = kk4[n][i] * rs; av[i] = -kk; bv[i] = kk * ic; kd[i] = k4[n][i] * (1.0f + (ic - 1.0f) * ka[i]); }
;         *(LAS f32x4*)(lw + fr * 64 + c) = av; *(LAS f32x4*)(lw + 3072 + fr * 64 + c) = wv; *(LAS f32x4*)(lw + (MODE == 3 ? 1024 : 4096) + fr * 64 + c) = bv;
;         if (MODE != 1) *(f32x4*)(srow + 192 + c) = kd;
;         { LAS float* xsel = (fr == (d ? 15 : 0)) ? lw + 2048 + c : lw + 2304 + lane * 4;
;           if (MODE != 1) *(LAS f32x4*)(xsel + 128) = kd; }
;         if (MODE == 2) { const f32x4 rk = *(const f32x4*)(P.r_k + col); const f32x4 t = r4[n] * kd * rk; bp += (t.x + t.y) + (t.z + t.w); }
;         if ((n & 1) == 1) asm volatile("" ::: "memory");
;     }
;     if (MODE == 2) { bp += shx(bp, 16, lane); bp += shx(bp, 32, lane); if (fq == 0) bon[(size_t)m * 8 + h] = 0.5f * bp; }
	v_pk_mul_f32 v[108:109], v[162:163], v[124:125] op_sel_hi:[1,0]
	v_mul_f32_e32 v98, 0xbf60028a, v98
	v_mul_f32_e32 v99, 0xbf60028a, v99
	v_pk_mul_f32 v[110:111], v[156:157], v[124:125] op_sel_hi:[1,0]
	v_exp_f32_e32 v96, v96
	v_exp_f32_e32 v97, v97
	v_xor_b32_e32 v105, 0x80000000, v109
	v_xor_b32_e32 v104, 0x80000000, v108
	v_exp_f32_e32 v98, v98
	v_exp_f32_e32 v99, v99
	v_xor_b32_e32 v106, 0x80000000, v110
	v_xor_b32_e32 v107, 0x80000000, v111
	v_pk_mul_f32 v[108:109], v[108:109], v[100:101]
	v_pk_mul_f32 v[110:111], v[110:111], v[102:103]
	v_pk_add_f32 v[102:103], v[102:103], -1.0 op_sel_hi:[1,0]
	v_pk_add_f32 v[100:101], v[100:101], -1.0 op_sel_hi:[1,0]
	v_pk_fma_f32 v[70:71], v[204:205], v[102:103], 1.0 op_sel_hi:[1,1,0]
	v_pk_fma_f32 v[68:69], v[202:203], v[100:101], 1.0 op_sel_hi:[1,1,0]
	v_pk_mul_f32 v[70:71], v[142:143], v[70:71]
	v_pk_mul_f32 v[68:69], v[144:145], v[68:69]
	ds_write_b128 v114, v[104:107] offset:64
	ds_write_b128 v114, v[96:99] offset:12352
	ds_write_b128 v114, v[108:111] offset:16448
	global_store_dwordx4 v[140:141], v[68:71], off offset:832
	s_nop 0
	v_pk_mul_f32 v[66:67], v[66:67], v[70:71]
	v_pk_mul_f32 v[64:65], v[64:65], v[68:69]
	ds_write_b128 v186, v[68:71] offset:512
	v_pk_mul_f32 v[66:67], v[118:119], v[66:67]
	v_pk_mul_f32 v[64:65], v[116:117], v[64:65]
	s_nop 0
	v_add_f32_e32 v64, v64, v65
	v_add_f32_e32 v65, v66, v67
	v_add_f32_e32 v64, v64, v65
	v_add_f32_e32 v100, v115, v64
	v_add_f32_e32 v68, v88, v214
	v_add_f32_e32 v69, v89, v215
	v_add_f32_e32 v70, v90, v216
	v_add_f32_e32 v71, v91, v217
	v_add_f32_e32 v92, v92, v228
	v_mul_f32_e32 v68, 0xbfb8aa3b, v68
	v_add_f32_e32 v88, v93, v229
	v_mul_f32_e32 v69, 0xbfb8aa3b, v69
	v_add_f32_e32 v94, v94, v230
	v_mul_f32_e32 v70, 0xbfb8aa3b, v70
	v_add_f32_e32 v90, v95, v231
	v_mul_f32_e32 v71, 0xbfb8aa3b, v71
	v_mul_f32_e32 v92, 0xbfb8aa3b, v92
	v_exp_f32_e32 v68, v68
	v_mul_f32_e32 v88, 0xbfb8aa3b, v88
	v_exp_f32_e32 v69, v69
	v_mul_f32_e32 v94, 0xbfb8aa3b, v94
	v_exp_f32_e32 v70, v70
	v_mul_f32_e32 v90, 0xbfb8aa3b, v90
	v_exp_f32_e32 v71, v71
	v_exp_f32_e32 v92, v92
	v_exp_f32_e32 v88, v88
	v_exp_f32_e32 v94, v94
	v_exp_f32_e32 v90, v90
	v_add_f32_e32 v68, 1.0, v68
	v_add_f32_e32 v69, 1.0, v69
	v_add_f32_e32 v70, 1.0, v70
	v_add_f32_e32 v71, 1.0, v71
	v_add_f32_e32 v92, 1.0, v92
	v_rcp_f32_e32 v68, v68
	v_add_f32_e32 v88, 1.0, v88
	v_rcp_f32_e32 v69, v69
	v_add_f32_e32 v94, 1.0, v94
	v_rcp_f32_e32 v70, v70
	v_add_f32_e32 v90, 1.0, v90
	v_rcp_f32_e32 v71, v71
	v_rcp_f32_e32 v96, v92
	v_rcp_f32_e32 v97, v88
	v_rcp_f32_e32 v98, v94
	v_rcp_f32_e32 v99, v90
	v_mul_f32_e32 v68, 0xbf60028a, v68
	v_mul_f32_e32 v69, 0xbf60028a, v69
	v_pk_mul_f32 v[92:93], v[172:173], v[124:125] op_sel_hi:[1,0]
	v_mul_f32_e32 v70, 0xbf60028a, v70
	v_mul_f32_e32 v71, 0xbf60028a, v71
	v_pk_mul_f32 v[94:95], v[168:169], v[124:125] op_sel_hi:[1,0]
	v_exp_f32_e32 v68, v68
	v_exp_f32_e32 v69, v69
	v_xor_b32_e32 v89, 0x80000000, v93
	v_xor_b32_e32 v88, 0x80000000, v92
	v_exp_f32_e32 v70, v70
	v_exp_f32_e32 v71, v71
	v_xor_b32_e32 v90, 0x80000000, v94
	v_xor_b32_e32 v91, 0x80000000, v95
	v_pk_mul_f32 v[92:93], v[92:93], v[96:97]
	v_pk_mul_f32 v[94:95], v[94:95], v[98:99]
	v_pk_add_f32 v[98:99], v[98:99], -1.0 op_sel_hi:[1,0]
	v_pk_add_f32 v[96:97], v[96:97], -1.0 op_sel_hi:[1,0]
	v_pk_fma_f32 v[66:67], v[234:235], v[98:99], 1.0 op_sel_hi:[1,1,0]
	v_pk_fma_f32 v[64:65], v[232:233], v[96:97], 1.0 op_sel_hi:[1,1,0]
	v_pk_mul_f32 v[66:67], v[146:147], v[66:67]
	v_pk_mul_f32 v[64:65], v[148:149], v[64:65]
	ds_write_b128 v114, v[88:91] offset:128
	ds_write_b128 v114, v[68:71] offset:12416
	ds_write_b128 v114, v[92:95] offset:16512
	global_store_dwordx4 v[140:141], v[64:67], off offset:896
	s_nop 0
	ds_write_b128 v189, v[64:67] offset:512
	v_pk_mul_f32 v[66:67], v[78:79], v[66:67]
	v_pk_mul_f32 v[64:65], v[76:77], v[64:65]
	v_pk_mul_f32 v[66:67], v[152:153], v[66:67]
	v_pk_mul_f32 v[64:65], v[150:151], v[64:65]
	s_nop 0
	v_add_f32_e32 v64, v64, v65
	v_add_f32_e32 v65, v66, v67
	v_add_f32_e32 v64, v64, v65
	v_add_f32_e32 v76, v100, v64
	v_add_f32_e32 v68, v80, v240
	v_add_f32_e32 v69, v81, v241
	v_add_f32_e32 v70, v82, v242
	v_add_f32_e32 v71, v83, v243
	v_mul_f32_e32 v68, 0xbfb8aa3b, v68
	v_mul_f32_e32 v69, 0xbfb8aa3b, v69
	v_mul_f32_e32 v70, 0xbfb8aa3b, v70
	v_mul_f32_e32 v71, 0xbfb8aa3b, v71
	v_exp_f32_e32 v68, v68
	v_exp_f32_e32 v69, v69
	v_exp_f32_e32 v70, v70
	v_exp_f32_e32 v71, v71
	v_add_f32_e32 v68, 1.0, v68
	v_add_f32_e32 v69, 1.0, v69
	v_add_f32_e32 v70, 1.0, v70
	v_add_f32_e32 v71, 1.0, v71
	v_rcp_f32_e32 v92, v68
	v_add_f32_e32 v68, v84, v244
	v_rcp_f32_e32 v93, v69
	v_add_f32_e32 v69, v85, v245
	v_rcp_f32_e32 v88, v70
	v_add_f32_e32 v70, v86, v246
	v_rcp_f32_e32 v89, v71
	v_add_f32_e32 v71, v87, v247
	v_mul_f32_e32 v68, 0xbfb8aa3b, v68
	v_mul_f32_e32 v69, 0xbfb8aa3b, v69
	v_mul_f32_e32 v70, 0xbfb8aa3b, v70
	v_mul_f32_e32 v71, 0xbfb8aa3b, v71
	v_exp_f32_e32 v68, v68
	v_exp_f32_e32 v69, v69
	v_exp_f32_e32 v70, v70
	v_exp_f32_e32 v71, v71
	v_add_f32_e32 v68, 1.0, v68
	v_add_f32_e32 v69, 1.0, v69
	v_add_f32_e32 v70, 1.0, v70
	v_add_f32_e32 v71, 1.0, v71
	v_rcp_f32_e32 v68, v68
	v_rcp_f32_e32 v69, v69
	v_rcp_f32_e32 v70, v70
	v_rcp_f32_e32 v71, v71
	v_mul_f32_e32 v68, 0xbf60028a, v68
	v_mul_f32_e32 v69, 0xbf60028a, v69
	v_pk_mul_f32 v[84:85], v[176:177], v[124:125] op_sel_hi:[1,0]
	v_mul_f32_e32 v70, 0xbf60028a, v70
	v_mul_f32_e32 v71, 0xbf60028a, v71
	v_pk_mul_f32 v[86:87], v[174:175], v[124:125] op_sel_hi:[1,0]
	v_exp_f32_e32 v68, v68
	v_exp_f32_e32 v69, v69
	v_xor_b32_e32 v79, 0x80000000, v85
	v_xor_b32_e32 v78, 0x80000000, v84
	v_exp_f32_e32 v70, v70
	v_exp_f32_e32 v71, v71
	v_xor_b32_e32 v80, 0x80000000, v86
	v_xor_b32_e32 v81, 0x80000000, v87
	v_pk_mul_f32 v[82:83], v[84:85], v[92:93]
	v_pk_mul_f32 v[84:85], v[86:87], v[88:89]
	v_pk_add_f32 v[86:87], v[88:89], -1.0 op_sel_hi:[1,0]
	v_pk_add_f32 v[88:89], v[92:93], -1.0 op_sel_hi:[1,0]
	v_pk_fma_f32 v[66:67], v[238:239], v[86:87], 1.0 op_sel_hi:[1,1,0]
	v_pk_fma_f32 v[64:65], v[236:237], v[88:89], 1.0 op_sel_hi:[1,1,0]
	v_pk_mul_f32 v[66:67], v[158:159], v[66:67]
	v_pk_mul_f32 v[64:65], v[160:161], v[64:65]
	ds_write_b128 v114, v[78:81] offset:192
	ds_write_b128 v114, v[68:71] offset:12480
	ds_write_b128 v114, v[82:85] offset:16576
	global_store_dwordx4 v[140:141], v[64:67], off offset:960
	s_nop 0
	ds_write_b128 v192, v[64:67] offset:512
	v_pk_mul_f32 v[66:67], v[74:75], v[66:67]
	v_pk_mul_f32 v[64:65], v[72:73], v[64:65]
	v_pk_mul_f32 v[66:67], v[166:167], v[66:67]
	v_pk_mul_f32 v[64:65], v[164:165], v[64:65]
	s_nop 0
	v_add_f32_e32 v64, v64, v65
	v_add_f32_e32 v65, v66, v67
	v_add_f32_e32 v64, v64, v65
	v_add_f32_e32 v64, v76, v64
	ds_bpermute_b32 v65, v191, v64
	s_waitcnt lgkmcnt(0)
	v_add_f32_e32 v64, v64, v65
	ds_bpermute_b32 v65, v190, v64
	s_and_saveexec_b64 s[4:5], vcc
	s_cbranch_execz .LBB0_551
	s_waitcnt lgkmcnt(0)
	v_add_f32_e32 v64, v64, v65
	v_mul_f32_e32 v66, 0.5, v64
	v_lshlrev_b64 v[64:65], 5, v[138:139]
	v_lshl_add_u64 v[64:65], s[80:81], 0, v[64:65]
	global_store_dword v[64:65], v66, off
